# per-segment s_setprio flips removed; one static s_setprio 1 for waves 4-7 at kernel entry
# baseline (speedup 1.0000x reference)
.LBB0_12:
	s_cmp_lt_u32 s80, 0x100
	s_cbranch_scc1 .Lprio_done
	s_setprio 1

.LBB0_181:
	ds_read_b128 v[128:131], v173
	ds_read_b128 v[132:135], v173 offset:1024
	ds_read_b128 v[136:139], v173 offset:2048
	ds_read_b128 v[140:143], v173 offset:3072
	ds_read_b128 v[162:165], v174
	ds_read_b128 v[166:169], v174 offset:1024
	ds_read_b128 v[176:179], v174 offset:2048
	ds_read_b128 v[180:183], v174 offset:3072
	s_add_u32 s6, s4, 0xfff80080
	s_addc_u32 s7, s5, -1
	s_cmp_eq_u32 s96, 28
	s_cselect_b32 s9, s26, s7
	s_cselect_b32 s8, s27, s6
	s_cselect_b32 s7, s86, s95
	s_cselect_b32 s6, s91, s94
	v_lshl_add_u64 v[216:217], s[4:5], 0, v[158:159]
	s_add_i32 m0, s47, 0xc000
	ds_read_b128 v[184:187], v175
	ds_read_b128 v[188:191], v175 offset:1024
	ds_read_b128 v[192:195], v175 offset:2048
	ds_read_b128 v[196:199], v175 offset:3072
	ds_read_b128 v[200:203], v175 offset:4096
	ds_read_b128 v[204:207], v175 offset:5120
	ds_read_b128 v[208:211], v175 offset:6144
	ds_read_b128 v[212:215], v175 offset:7168
	global_load_lds_dwordx4 v[216:217], off
	v_lshl_add_u64 v[216:217], s[4:5], 0, v[160:161]
	s_add_i32 m0, s47, 0xe000
	s_nop 0
	global_load_lds_dwordx4 v[216:217], off
	s_waitcnt vmcnt(8)
	s_waitcnt lgkmcnt(0)
	s_barrier
	s_waitcnt lgkmcnt(0)
	v_mfma_f32_16x16x32_bf16 v[124:127], v[128:131], v[184:187], v[124:127]
	v_mfma_f32_16x16x32_bf16 v[120:123], v[136:139], v[184:187], v[120:123]
	v_mfma_f32_16x16x32_bf16 v[108:111], v[128:131], v[192:195], v[108:111]
	v_mfma_f32_16x16x32_bf16 v[104:107], v[136:139], v[192:195], v[104:107]
	v_mfma_f32_16x16x32_bf16 v[92:95], v[128:131], v[200:203], v[92:95]
	v_mfma_f32_16x16x32_bf16 v[88:91], v[136:139], v[200:203], v[88:91]
	v_mfma_f32_16x16x32_bf16 v[76:79], v[128:131], v[208:211], v[76:79]
	v_mfma_f32_16x16x32_bf16 v[72:75], v[136:139], v[208:211], v[72:75]
	v_mfma_f32_16x16x32_bf16 v[124:127], v[132:135], v[188:191], v[124:127]
	v_mfma_f32_16x16x32_bf16 v[120:123], v[140:143], v[188:191], v[120:123]
	v_mfma_f32_16x16x32_bf16 v[108:111], v[132:135], v[196:199], v[108:111]
	v_mfma_f32_16x16x32_bf16 v[104:107], v[140:143], v[196:199], v[104:107]
	v_mfma_f32_16x16x32_bf16 v[92:95], v[132:135], v[204:207], v[92:95]
	v_mfma_f32_16x16x32_bf16 v[88:91], v[140:143], v[204:207], v[88:91]
	v_mfma_f32_16x16x32_bf16 v[76:79], v[132:135], v[212:215], v[76:79]
	v_mfma_f32_16x16x32_bf16 v[72:75], v[140:143], v[212:215], v[72:75]
	v_mfma_f32_16x16x32_bf16 v[116:119], v[162:165], v[184:187], v[116:119]
	v_mfma_f32_16x16x32_bf16 v[112:115], v[176:179], v[184:187], v[112:115]
	v_mfma_f32_16x16x32_bf16 v[100:103], v[162:165], v[192:195], v[100:103]
	v_mfma_f32_16x16x32_bf16 v[96:99], v[176:179], v[192:195], v[96:99]
	v_mfma_f32_16x16x32_bf16 v[84:87], v[162:165], v[200:203], v[84:87]
	v_mfma_f32_16x16x32_bf16 v[80:83], v[176:179], v[200:203], v[80:83]
	v_mfma_f32_16x16x32_bf16 v[68:71], v[162:165], v[208:211], v[68:71]
	v_mfma_f32_16x16x32_bf16 v[64:67], v[176:179], v[208:211], v[64:67]
	v_mfma_f32_16x16x32_bf16 v[116:119], v[166:169], v[188:191], v[116:119]
	v_mfma_f32_16x16x32_bf16 v[112:115], v[180:183], v[188:191], v[112:115]
	v_mfma_f32_16x16x32_bf16 v[100:103], v[166:169], v[196:199], v[100:103]
	v_mfma_f32_16x16x32_bf16 v[96:99], v[180:183], v[196:199], v[96:99]
	v_mfma_f32_16x16x32_bf16 v[84:87], v[166:169], v[204:207], v[84:87]
	v_mfma_f32_16x16x32_bf16 v[80:83], v[180:183], v[204:207], v[80:83]
	v_mfma_f32_16x16x32_bf16 v[68:71], v[166:169], v[212:215], v[68:71]
	v_mfma_f32_16x16x32_bf16 v[64:67], v[180:183], v[212:215], v[64:67]
	s_barrier
	s_add_i32 s97, s30, s44
	v_lshl_add_u64 v[216:217], s[6:7], 0, v[146:147]
	s_mov_b32 m0, s97
	ds_read_b128 v[184:187], v175 offset:16384
	ds_read_b128 v[188:191], v175 offset:17408
	ds_read_b128 v[192:195], v175 offset:18432
	ds_read_b128 v[196:199], v175 offset:19456
	ds_read_b128 v[200:203], v175 offset:20480
	ds_read_b128 v[204:207], v175 offset:21504
	ds_read_b128 v[208:211], v175 offset:22528
	ds_read_b128 v[212:215], v175 offset:23552
	global_load_lds_dwordx4 v[216:217], off
	s_add_i32 m0, s97, 0x2000
	s_add_u32 vcc_lo, s6, 0x80000
	v_lshl_add_u64 v[218:219], s[6:7], 0, v[144:145]
	s_addc_u32 vcc_hi, s7, 0
	s_add_i32 s97, s31, s44
	global_load_lds_dwordx4 v[218:219], off
	v_lshl_add_u64 v[220:221], vcc, 0, v[146:147]
	s_mov_b32 m0, s97
	v_lshl_add_u64 v[222:223], s[8:9], 0, v[144:145]
	global_load_lds_dwordx4 v[220:221], off
	v_lshl_add_u64 v[220:221], vcc, 0, v[144:145]
	s_add_i32 m0, s97, 0x2000
	s_nop 0
	global_load_lds_dwordx4 v[220:221], off
	v_lshl_add_u64 v[220:221], s[8:9], 0, v[146:147]
	s_mov_b32 m0, s47
	s_nop 0
	global_load_lds_dwordx4 v[220:221], off
	s_mov_b32 m0, s48
	s_nop 0
	global_load_lds_dwordx4 v[222:223], off
	s_waitcnt vmcnt(8)
	s_waitcnt lgkmcnt(0)
	s_barrier
	s_waitcnt lgkmcnt(0)
	v_mfma_f32_16x16x32_bf16 v[60:63], v[128:131], v[184:187], v[60:63]
	v_mfma_f32_16x16x32_bf16 v[56:59], v[136:139], v[184:187], v[56:59]
	v_mfma_f32_16x16x32_bf16 v[44:47], v[128:131], v[192:195], v[44:47]
	v_mfma_f32_16x16x32_bf16 v[40:43], v[136:139], v[192:195], v[40:43]
	v_mfma_f32_16x16x32_bf16 v[28:31], v[128:131], v[200:203], v[28:31]
	v_mfma_f32_16x16x32_bf16 v[24:27], v[136:139], v[200:203], v[24:27]
	v_mfma_f32_16x16x32_bf16 v[12:15], v[128:131], v[208:211], v[12:15]
	v_mfma_f32_16x16x32_bf16 v[8:11], v[136:139], v[208:211], v[8:11]
	v_mfma_f32_16x16x32_bf16 v[60:63], v[132:135], v[188:191], v[60:63]
	v_mfma_f32_16x16x32_bf16 v[56:59], v[140:143], v[188:191], v[56:59]
	v_mfma_f32_16x16x32_bf16 v[44:47], v[132:135], v[196:199], v[44:47]
	v_mfma_f32_16x16x32_bf16 v[40:43], v[140:143], v[196:199], v[40:43]
	v_mfma_f32_16x16x32_bf16 v[28:31], v[132:135], v[204:207], v[28:31]
	v_mfma_f32_16x16x32_bf16 v[24:27], v[140:143], v[204:207], v[24:27]
	v_mfma_f32_16x16x32_bf16 v[12:15], v[132:135], v[212:215], v[12:15]
	v_mfma_f32_16x16x32_bf16 v[8:11], v[140:143], v[212:215], v[8:11]
	v_mfma_f32_16x16x32_bf16 v[52:55], v[162:165], v[184:187], v[52:55]
	v_mfma_f32_16x16x32_bf16 v[48:51], v[176:179], v[184:187], v[48:51]
	v_mfma_f32_16x16x32_bf16 v[36:39], v[162:165], v[192:195], v[36:39]
	v_mfma_f32_16x16x32_bf16 v[32:35], v[176:179], v[192:195], v[32:35]
	v_mfma_f32_16x16x32_bf16 v[20:23], v[162:165], v[200:203], v[20:23]
	v_mfma_f32_16x16x32_bf16 v[16:19], v[176:179], v[200:203], v[16:19]
	v_mfma_f32_16x16x32_bf16 v[4:7], v[162:165], v[208:211], v[4:7]
	v_mfma_f32_16x16x32_bf16 v[0:3], v[176:179], v[208:211], v[0:3]
	v_mfma_f32_16x16x32_bf16 v[52:55], v[166:169], v[188:191], v[52:55]
	v_mfma_f32_16x16x32_bf16 v[48:51], v[180:183], v[188:191], v[48:51]
	v_mfma_f32_16x16x32_bf16 v[36:39], v[166:169], v[196:199], v[36:39]
	v_mfma_f32_16x16x32_bf16 v[32:35], v[180:183], v[196:199], v[32:35]
	v_mfma_f32_16x16x32_bf16 v[20:23], v[166:169], v[204:207], v[20:23]
	v_mfma_f32_16x16x32_bf16 v[16:19], v[180:183], v[204:207], v[16:19]
	v_mfma_f32_16x16x32_bf16 v[4:7], v[166:169], v[212:215], v[4:7]
	v_mfma_f32_16x16x32_bf16 v[0:3], v[180:183], v[212:215], v[0:3]
	s_barrier
	s_add_i32 s97, 0, 0x18000
	s_add_i32 vcc_lo, 0, 0x1c000
	v_add_u32_e32 v140, s97, v153
	v_add_u32_e32 v180, vcc_lo, v153
	ds_read_b128 v[128:131], v140
	ds_read_b128 v[132:135], v140 offset:1024
	ds_read_b128 v[136:139], v140 offset:2048
	ds_read_b128 v[140:143], v140 offset:3072
	ds_read_b128 v[162:165], v180
	ds_read_b128 v[166:169], v180 offset:1024
	ds_read_b128 v[176:179], v180 offset:2048
	ds_read_b128 v[180:183], v180 offset:3072
	s_add_u32 s8, s8, 0x80000
	s_addc_u32 s9, s9, 0
	s_mov_b32 m0, s49
	v_lshl_add_u64 v[224:225], s[8:9], 0, v[146:147]
	ds_read_b128 v[184:187], v175 offset:32768
	ds_read_b128 v[188:191], v175 offset:33792
	ds_read_b128 v[192:195], v175 offset:34816
	ds_read_b128 v[196:199], v175 offset:35840
	ds_read_b128 v[200:203], v175 offset:36864
	ds_read_b128 v[204:207], v175 offset:37888
	ds_read_b128 v[208:211], v175 offset:38912
	ds_read_b128 v[212:215], v175 offset:39936
	global_load_lds_dwordx4 v[224:225], off
	v_lshl_add_u64 v[224:225], s[8:9], 0, v[144:145]
	s_mov_b32 m0, s50
	s_nop 0
	global_load_lds_dwordx4 v[224:225], off
	s_waitcnt vmcnt(8)
	s_waitcnt lgkmcnt(0)
	s_barrier
	s_waitcnt lgkmcnt(0)
	v_mfma_f32_16x16x32_bf16 v[124:127], v[128:131], v[184:187], v[124:127]
	v_mfma_f32_16x16x32_bf16 v[120:123], v[136:139], v[184:187], v[120:123]
	v_mfma_f32_16x16x32_bf16 v[108:111], v[128:131], v[192:195], v[108:111]
	v_mfma_f32_16x16x32_bf16 v[104:107], v[136:139], v[192:195], v[104:107]
	v_mfma_f32_16x16x32_bf16 v[92:95], v[128:131], v[200:203], v[92:95]
	v_mfma_f32_16x16x32_bf16 v[88:91], v[136:139], v[200:203], v[88:91]
	v_mfma_f32_16x16x32_bf16 v[76:79], v[128:131], v[208:211], v[76:79]
	v_mfma_f32_16x16x32_bf16 v[72:75], v[136:139], v[208:211], v[72:75]
	v_mfma_f32_16x16x32_bf16 v[124:127], v[132:135], v[188:191], v[124:127]
	v_mfma_f32_16x16x32_bf16 v[120:123], v[140:143], v[188:191], v[120:123]
	v_mfma_f32_16x16x32_bf16 v[108:111], v[132:135], v[196:199], v[108:111]
	v_mfma_f32_16x16x32_bf16 v[104:107], v[140:143], v[196:199], v[104:107]
	v_mfma_f32_16x16x32_bf16 v[92:95], v[132:135], v[204:207], v[92:95]
	v_mfma_f32_16x16x32_bf16 v[88:91], v[140:143], v[204:207], v[88:91]
	v_mfma_f32_16x16x32_bf16 v[76:79], v[132:135], v[212:215], v[76:79]
	v_mfma_f32_16x16x32_bf16 v[72:75], v[140:143], v[212:215], v[72:75]
	v_mfma_f32_16x16x32_bf16 v[116:119], v[162:165], v[184:187], v[116:119]
	v_mfma_f32_16x16x32_bf16 v[112:115], v[176:179], v[184:187], v[112:115]
	v_mfma_f32_16x16x32_bf16 v[100:103], v[162:165], v[192:195], v[100:103]
	v_mfma_f32_16x16x32_bf16 v[96:99], v[176:179], v[192:195], v[96:99]
	v_mfma_f32_16x16x32_bf16 v[84:87], v[162:165], v[200:203], v[84:87]
	v_mfma_f32_16x16x32_bf16 v[80:83], v[176:179], v[200:203], v[80:83]
	v_mfma_f32_16x16x32_bf16 v[68:71], v[162:165], v[208:211], v[68:71]
	v_mfma_f32_16x16x32_bf16 v[64:67], v[176:179], v[208:211], v[64:67]
	v_mfma_f32_16x16x32_bf16 v[116:119], v[166:169], v[188:191], v[116:119]
	v_mfma_f32_16x16x32_bf16 v[112:115], v[180:183], v[188:191], v[112:115]
	v_mfma_f32_16x16x32_bf16 v[100:103], v[166:169], v[196:199], v[100:103]
	v_mfma_f32_16x16x32_bf16 v[96:99], v[180:183], v[196:199], v[96:99]
	v_mfma_f32_16x16x32_bf16 v[84:87], v[166:169], v[204:207], v[84:87]
	v_mfma_f32_16x16x32_bf16 v[80:83], v[180:183], v[204:207], v[80:83]
	v_mfma_f32_16x16x32_bf16 v[68:71], v[166:169], v[212:215], v[68:71]
	v_mfma_f32_16x16x32_bf16 v[64:67], v[180:183], v[212:215], v[64:67]
	s_barrier
	s_add_i32 s8, s97, s44
	v_lshl_add_u64 v[216:217], v[216:217], 0, s[78:79]
	s_mov_b32 m0, s8
	ds_read_b128 v[184:187], v175 offset:49152
	ds_read_b128 v[188:191], v175 offset:50176
	ds_read_b128 v[192:195], v175 offset:51200
	ds_read_b128 v[196:199], v175 offset:52224
	ds_read_b128 v[200:203], v175 offset:53248
	ds_read_b128 v[204:207], v175 offset:54272
	ds_read_b128 v[208:211], v175 offset:55296
	ds_read_b128 v[212:215], v175 offset:56320
	global_load_lds_dwordx4 v[216:217], off
	s_add_i32 m0, s8, 0x2000
	s_add_u32 s6, s6, 0x80080
	v_lshl_add_u64 v[216:217], v[218:219], 0, s[78:79]
	s_addc_u32 s7, s7, 0
	s_add_i32 s8, vcc_lo, s44
	global_load_lds_dwordx4 v[216:217], off
	v_lshl_add_u64 v[216:217], s[6:7], 0, v[146:147]
	s_mov_b32 m0, s8
	s_nop 0
	global_load_lds_dwordx4 v[216:217], off
	v_lshl_add_u64 v[216:217], s[6:7], 0, v[144:145]
	s_add_i32 m0, s8, 0x2000
	s_nop 0
	global_load_lds_dwordx4 v[216:217], off
	v_lshl_add_u64 v[216:217], v[220:221], 0, s[78:79]
	s_mov_b32 m0, s71
	s_nop 0
	global_load_lds_dwordx4 v[216:217], off
	v_lshl_add_u64 v[216:217], v[222:223], 0, s[78:79]
	s_mov_b32 m0, s84
	s_nop 0
	global_load_lds_dwordx4 v[216:217], off
	s_waitcnt vmcnt(8)
	s_waitcnt lgkmcnt(0)
	s_barrier
	s_waitcnt lgkmcnt(0)
	v_mfma_f32_16x16x32_bf16 v[60:63], v[128:131], v[184:187], v[60:63]
	v_mfma_f32_16x16x32_bf16 v[56:59], v[136:139], v[184:187], v[56:59]
	v_mfma_f32_16x16x32_bf16 v[44:47], v[128:131], v[192:195], v[44:47]
	v_mfma_f32_16x16x32_bf16 v[40:43], v[136:139], v[192:195], v[40:43]
	v_mfma_f32_16x16x32_bf16 v[28:31], v[128:131], v[200:203], v[28:31]
	v_mfma_f32_16x16x32_bf16 v[24:27], v[136:139], v[200:203], v[24:27]
	v_mfma_f32_16x16x32_bf16 v[12:15], v[128:131], v[208:211], v[12:15]
	v_mfma_f32_16x16x32_bf16 v[8:11], v[136:139], v[208:211], v[8:11]
	v_mfma_f32_16x16x32_bf16 v[60:63], v[132:135], v[188:191], v[60:63]
	v_mfma_f32_16x16x32_bf16 v[56:59], v[140:143], v[188:191], v[56:59]
	v_mfma_f32_16x16x32_bf16 v[44:47], v[132:135], v[196:199], v[44:47]
	v_mfma_f32_16x16x32_bf16 v[40:43], v[140:143], v[196:199], v[40:43]
	v_mfma_f32_16x16x32_bf16 v[28:31], v[132:135], v[204:207], v[28:31]
	v_mfma_f32_16x16x32_bf16 v[24:27], v[140:143], v[204:207], v[24:27]
	v_mfma_f32_16x16x32_bf16 v[12:15], v[132:135], v[212:215], v[12:15]
	v_mfma_f32_16x16x32_bf16 v[8:11], v[140:143], v[212:215], v[8:11]
	v_mfma_f32_16x16x32_bf16 v[52:55], v[162:165], v[184:187], v[52:55]
	v_mfma_f32_16x16x32_bf16 v[48:51], v[176:179], v[184:187], v[48:51]
	v_mfma_f32_16x16x32_bf16 v[36:39], v[162:165], v[192:195], v[36:39]
	v_mfma_f32_16x16x32_bf16 v[32:35], v[176:179], v[192:195], v[32:35]
	v_mfma_f32_16x16x32_bf16 v[20:23], v[162:165], v[200:203], v[20:23]
	v_mfma_f32_16x16x32_bf16 v[16:19], v[176:179], v[200:203], v[16:19]
	v_mfma_f32_16x16x32_bf16 v[4:7], v[162:165], v[208:211], v[4:7]
	v_mfma_f32_16x16x32_bf16 v[0:3], v[176:179], v[208:211], v[0:3]
	v_mfma_f32_16x16x32_bf16 v[52:55], v[166:169], v[188:191], v[52:55]
	v_mfma_f32_16x16x32_bf16 v[48:51], v[180:183], v[188:191], v[48:51]
	v_mfma_f32_16x16x32_bf16 v[36:39], v[166:169], v[196:199], v[36:39]
	v_mfma_f32_16x16x32_bf16 v[32:35], v[180:183], v[196:199], v[32:35]
	v_mfma_f32_16x16x32_bf16 v[20:23], v[166:169], v[204:207], v[20:23]
	v_mfma_f32_16x16x32_bf16 v[16:19], v[180:183], v[204:207], v[16:19]
	v_mfma_f32_16x16x32_bf16 v[4:7], v[166:169], v[212:215], v[4:7]
	v_mfma_f32_16x16x32_bf16 v[0:3], v[180:183], v[212:215], v[0:3]
	s_barrier
	s_add_i32 s96, s96, 2
	s_add_u32 s4, s4, 0x100
	s_addc_u32 s5, s5, 0
	s_add_u32 s94, s94, 0x100
	s_addc_u32 s95, s95, 0
	s_cmp_gt_u32 s96, 29
	s_cbranch_scc0 .LBB0_181
	s_and_b64 vcc, exec, s[88:89]
	s_cbranch_vccz .LBB0_184
	s_barrier

.LBB0_468:
	ds_read_b128 v[128:131], v173
	ds_read_b128 v[132:135], v173 offset:1024
	ds_read_b128 v[136:139], v173 offset:2048
	ds_read_b128 v[140:143], v173 offset:3072
	ds_read_b128 v[162:165], v174
	ds_read_b128 v[166:169], v174 offset:1024
	ds_read_b128 v[176:179], v174 offset:2048
	ds_read_b128 v[180:183], v174 offset:3072
	s_add_u32 s6, s4, 0xfff80080
	s_addc_u32 s7, s5, -1
	s_cmp_eq_u32 s85, 28
	s_cselect_b32 s9, s26, s7
	s_cselect_b32 s8, s27, s6
	s_cselect_b32 s7, s35, s84
	s_cselect_b32 s6, s68, s77
	v_lshl_add_u64 v[216:217], s[4:5], 0, v[158:159]
	s_add_i32 m0, s44, 0xc000
	ds_read_b128 v[184:187], v175
	ds_read_b128 v[188:191], v175 offset:1024
	ds_read_b128 v[192:195], v175 offset:2048
	ds_read_b128 v[196:199], v175 offset:3072
	ds_read_b128 v[200:203], v175 offset:4096
	ds_read_b128 v[204:207], v175 offset:5120
	ds_read_b128 v[208:211], v175 offset:6144
	ds_read_b128 v[212:215], v175 offset:7168
	global_load_lds_dwordx4 v[216:217], off
	v_lshl_add_u64 v[216:217], s[4:5], 0, v[160:161]
	s_add_i32 m0, s44, 0xe000
	s_nop 0
	global_load_lds_dwordx4 v[216:217], off
	s_waitcnt vmcnt(8)
	s_waitcnt lgkmcnt(0)
	s_barrier
	s_waitcnt lgkmcnt(0)
	v_mfma_f32_16x16x32_bf16 v[124:127], v[128:131], v[184:187], v[124:127]
	v_mfma_f32_16x16x32_bf16 v[120:123], v[136:139], v[184:187], v[120:123]
	v_mfma_f32_16x16x32_bf16 v[108:111], v[128:131], v[192:195], v[108:111]
	v_mfma_f32_16x16x32_bf16 v[104:107], v[136:139], v[192:195], v[104:107]
	v_mfma_f32_16x16x32_bf16 v[92:95], v[128:131], v[200:203], v[92:95]
	v_mfma_f32_16x16x32_bf16 v[88:91], v[136:139], v[200:203], v[88:91]
	v_mfma_f32_16x16x32_bf16 v[76:79], v[128:131], v[208:211], v[76:79]
	v_mfma_f32_16x16x32_bf16 v[72:75], v[136:139], v[208:211], v[72:75]
	v_mfma_f32_16x16x32_bf16 v[124:127], v[132:135], v[188:191], v[124:127]
	v_mfma_f32_16x16x32_bf16 v[120:123], v[140:143], v[188:191], v[120:123]
	v_mfma_f32_16x16x32_bf16 v[108:111], v[132:135], v[196:199], v[108:111]
	v_mfma_f32_16x16x32_bf16 v[104:107], v[140:143], v[196:199], v[104:107]
	v_mfma_f32_16x16x32_bf16 v[92:95], v[132:135], v[204:207], v[92:95]
	v_mfma_f32_16x16x32_bf16 v[88:91], v[140:143], v[204:207], v[88:91]
	v_mfma_f32_16x16x32_bf16 v[76:79], v[132:135], v[212:215], v[76:79]
	v_mfma_f32_16x16x32_bf16 v[72:75], v[140:143], v[212:215], v[72:75]
	v_mfma_f32_16x16x32_bf16 v[116:119], v[162:165], v[184:187], v[116:119]
	v_mfma_f32_16x16x32_bf16 v[112:115], v[176:179], v[184:187], v[112:115]
	v_mfma_f32_16x16x32_bf16 v[100:103], v[162:165], v[192:195], v[100:103]
	v_mfma_f32_16x16x32_bf16 v[96:99], v[176:179], v[192:195], v[96:99]
	v_mfma_f32_16x16x32_bf16 v[84:87], v[162:165], v[200:203], v[84:87]
	v_mfma_f32_16x16x32_bf16 v[80:83], v[176:179], v[200:203], v[80:83]
	v_mfma_f32_16x16x32_bf16 v[68:71], v[162:165], v[208:211], v[68:71]
	v_mfma_f32_16x16x32_bf16 v[64:67], v[176:179], v[208:211], v[64:67]
	v_mfma_f32_16x16x32_bf16 v[116:119], v[166:169], v[188:191], v[116:119]
	v_mfma_f32_16x16x32_bf16 v[112:115], v[180:183], v[188:191], v[112:115]
	v_mfma_f32_16x16x32_bf16 v[100:103], v[166:169], v[196:199], v[100:103]
	v_mfma_f32_16x16x32_bf16 v[96:99], v[180:183], v[196:199], v[96:99]
	v_mfma_f32_16x16x32_bf16 v[84:87], v[166:169], v[204:207], v[84:87]
	v_mfma_f32_16x16x32_bf16 v[80:83], v[180:183], v[204:207], v[80:83]
	v_mfma_f32_16x16x32_bf16 v[68:71], v[166:169], v[212:215], v[68:71]
	v_mfma_f32_16x16x32_bf16 v[64:67], v[180:183], v[212:215], v[64:67]
	s_barrier
	s_add_i32 s89, s51, s43
	v_lshl_add_u64 v[216:217], s[6:7], 0, v[144:145]
	s_mov_b32 m0, s89
	ds_read_b128 v[184:187], v175 offset:16384
	ds_read_b128 v[188:191], v175 offset:17408
	ds_read_b128 v[192:195], v175 offset:18432
	ds_read_b128 v[196:199], v175 offset:19456
	ds_read_b128 v[200:203], v175 offset:20480
	ds_read_b128 v[204:207], v175 offset:21504
	ds_read_b128 v[208:211], v175 offset:22528
	ds_read_b128 v[212:215], v175 offset:23552
	global_load_lds_dwordx4 v[216:217], off
	s_add_i32 m0, s89, 0x2000
	s_add_u32 s90, s6, 0x80000
	v_lshl_add_u64 v[218:219], s[6:7], 0, v[146:147]
	s_addc_u32 s91, s7, 0
	s_add_i32 s89, s65, s43
	global_load_lds_dwordx4 v[218:219], off
	v_lshl_add_u64 v[220:221], s[90:91], 0, v[144:145]
	s_mov_b32 m0, s89
	v_lshl_add_u64 v[222:223], s[8:9], 0, v[146:147]
	global_load_lds_dwordx4 v[220:221], off
	v_lshl_add_u64 v[220:221], s[90:91], 0, v[146:147]
	s_add_i32 m0, s89, 0x2000
	s_nop 0
	global_load_lds_dwordx4 v[220:221], off
	v_lshl_add_u64 v[220:221], s[8:9], 0, v[144:145]
	s_mov_b32 m0, s44
	s_nop 0
	global_load_lds_dwordx4 v[220:221], off
	s_mov_b32 m0, s45
	s_nop 0
	global_load_lds_dwordx4 v[222:223], off
	s_waitcnt vmcnt(8)
	s_waitcnt lgkmcnt(0)
	s_barrier
	s_waitcnt lgkmcnt(0)
	v_mfma_f32_16x16x32_bf16 v[60:63], v[128:131], v[184:187], v[60:63]
	v_mfma_f32_16x16x32_bf16 v[56:59], v[136:139], v[184:187], v[56:59]
	v_mfma_f32_16x16x32_bf16 v[44:47], v[128:131], v[192:195], v[44:47]
	v_mfma_f32_16x16x32_bf16 v[40:43], v[136:139], v[192:195], v[40:43]
	v_mfma_f32_16x16x32_bf16 v[28:31], v[128:131], v[200:203], v[28:31]
	v_mfma_f32_16x16x32_bf16 v[24:27], v[136:139], v[200:203], v[24:27]
	v_mfma_f32_16x16x32_bf16 v[12:15], v[128:131], v[208:211], v[12:15]
	v_mfma_f32_16x16x32_bf16 v[8:11], v[136:139], v[208:211], v[8:11]
	v_mfma_f32_16x16x32_bf16 v[60:63], v[132:135], v[188:191], v[60:63]
	v_mfma_f32_16x16x32_bf16 v[56:59], v[140:143], v[188:191], v[56:59]
	v_mfma_f32_16x16x32_bf16 v[44:47], v[132:135], v[196:199], v[44:47]
	v_mfma_f32_16x16x32_bf16 v[40:43], v[140:143], v[196:199], v[40:43]
	v_mfma_f32_16x16x32_bf16 v[28:31], v[132:135], v[204:207], v[28:31]
	v_mfma_f32_16x16x32_bf16 v[24:27], v[140:143], v[204:207], v[24:27]
	v_mfma_f32_16x16x32_bf16 v[12:15], v[132:135], v[212:215], v[12:15]
	v_mfma_f32_16x16x32_bf16 v[8:11], v[140:143], v[212:215], v[8:11]
	v_mfma_f32_16x16x32_bf16 v[52:55], v[162:165], v[184:187], v[52:55]
	v_mfma_f32_16x16x32_bf16 v[48:51], v[176:179], v[184:187], v[48:51]
	v_mfma_f32_16x16x32_bf16 v[36:39], v[162:165], v[192:195], v[36:39]
	v_mfma_f32_16x16x32_bf16 v[32:35], v[176:179], v[192:195], v[32:35]
	v_mfma_f32_16x16x32_bf16 v[20:23], v[162:165], v[200:203], v[20:23]
	v_mfma_f32_16x16x32_bf16 v[16:19], v[176:179], v[200:203], v[16:19]
	v_mfma_f32_16x16x32_bf16 v[4:7], v[162:165], v[208:211], v[4:7]
	v_mfma_f32_16x16x32_bf16 v[0:3], v[176:179], v[208:211], v[0:3]
	v_mfma_f32_16x16x32_bf16 v[52:55], v[166:169], v[188:191], v[52:55]
	v_mfma_f32_16x16x32_bf16 v[48:51], v[180:183], v[188:191], v[48:51]
	v_mfma_f32_16x16x32_bf16 v[36:39], v[166:169], v[196:199], v[36:39]
	v_mfma_f32_16x16x32_bf16 v[32:35], v[180:183], v[196:199], v[32:35]
	v_mfma_f32_16x16x32_bf16 v[20:23], v[166:169], v[204:207], v[20:23]
	v_mfma_f32_16x16x32_bf16 v[16:19], v[180:183], v[204:207], v[16:19]
	v_mfma_f32_16x16x32_bf16 v[4:7], v[166:169], v[212:215], v[4:7]
	v_mfma_f32_16x16x32_bf16 v[0:3], v[180:183], v[212:215], v[0:3]
	s_barrier
	s_add_i32 s89, 0, 0x18000
	s_add_i32 s90, 0, 0x1c000
	v_add_u32_e32 v140, s89, v153
	v_add_u32_e32 v180, s90, v153
	ds_read_b128 v[128:131], v140
	ds_read_b128 v[132:135], v140 offset:1024
	ds_read_b128 v[136:139], v140 offset:2048
	ds_read_b128 v[140:143], v140 offset:3072
	ds_read_b128 v[162:165], v180
	ds_read_b128 v[166:169], v180 offset:1024
	ds_read_b128 v[176:179], v180 offset:2048
	ds_read_b128 v[180:183], v180 offset:3072
	s_add_u32 s8, s8, 0x80000
	s_addc_u32 s9, s9, 0
	s_mov_b32 m0, s46
	v_lshl_add_u64 v[224:225], s[8:9], 0, v[144:145]
	ds_read_b128 v[184:187], v175 offset:32768
	ds_read_b128 v[188:191], v175 offset:33792
	ds_read_b128 v[192:195], v175 offset:34816
	ds_read_b128 v[196:199], v175 offset:35840
	ds_read_b128 v[200:203], v175 offset:36864
	ds_read_b128 v[204:207], v175 offset:37888
	ds_read_b128 v[208:211], v175 offset:38912
	ds_read_b128 v[212:215], v175 offset:39936
	global_load_lds_dwordx4 v[224:225], off
	v_lshl_add_u64 v[224:225], s[8:9], 0, v[146:147]
	s_mov_b32 m0, s47
	s_nop 0
	global_load_lds_dwordx4 v[224:225], off
	s_waitcnt vmcnt(8)
	s_waitcnt lgkmcnt(0)
	s_barrier
	s_waitcnt lgkmcnt(0)
	v_mfma_f32_16x16x32_bf16 v[124:127], v[128:131], v[184:187], v[124:127]
	v_mfma_f32_16x16x32_bf16 v[120:123], v[136:139], v[184:187], v[120:123]
	v_mfma_f32_16x16x32_bf16 v[108:111], v[128:131], v[192:195], v[108:111]
	v_mfma_f32_16x16x32_bf16 v[104:107], v[136:139], v[192:195], v[104:107]
	v_mfma_f32_16x16x32_bf16 v[92:95], v[128:131], v[200:203], v[92:95]
	v_mfma_f32_16x16x32_bf16 v[88:91], v[136:139], v[200:203], v[88:91]
	v_mfma_f32_16x16x32_bf16 v[76:79], v[128:131], v[208:211], v[76:79]
	v_mfma_f32_16x16x32_bf16 v[72:75], v[136:139], v[208:211], v[72:75]
	v_mfma_f32_16x16x32_bf16 v[124:127], v[132:135], v[188:191], v[124:127]
	v_mfma_f32_16x16x32_bf16 v[120:123], v[140:143], v[188:191], v[120:123]
	v_mfma_f32_16x16x32_bf16 v[108:111], v[132:135], v[196:199], v[108:111]
	v_mfma_f32_16x16x32_bf16 v[104:107], v[140:143], v[196:199], v[104:107]
	v_mfma_f32_16x16x32_bf16 v[92:95], v[132:135], v[204:207], v[92:95]
	v_mfma_f32_16x16x32_bf16 v[88:91], v[140:143], v[204:207], v[88:91]
	v_mfma_f32_16x16x32_bf16 v[76:79], v[132:135], v[212:215], v[76:79]
	v_mfma_f32_16x16x32_bf16 v[72:75], v[140:143], v[212:215], v[72:75]
	v_mfma_f32_16x16x32_bf16 v[116:119], v[162:165], v[184:187], v[116:119]
	v_mfma_f32_16x16x32_bf16 v[112:115], v[176:179], v[184:187], v[112:115]
	v_mfma_f32_16x16x32_bf16 v[100:103], v[162:165], v[192:195], v[100:103]
	v_mfma_f32_16x16x32_bf16 v[96:99], v[176:179], v[192:195], v[96:99]
	v_mfma_f32_16x16x32_bf16 v[84:87], v[162:165], v[200:203], v[84:87]
	v_mfma_f32_16x16x32_bf16 v[80:83], v[176:179], v[200:203], v[80:83]
	v_mfma_f32_16x16x32_bf16 v[68:71], v[162:165], v[208:211], v[68:71]
	v_mfma_f32_16x16x32_bf16 v[64:67], v[176:179], v[208:211], v[64:67]
	v_mfma_f32_16x16x32_bf16 v[116:119], v[166:169], v[188:191], v[116:119]
	v_mfma_f32_16x16x32_bf16 v[112:115], v[180:183], v[188:191], v[112:115]
	v_mfma_f32_16x16x32_bf16 v[100:103], v[166:169], v[196:199], v[100:103]
	v_mfma_f32_16x16x32_bf16 v[96:99], v[180:183], v[196:199], v[96:99]
	v_mfma_f32_16x16x32_bf16 v[84:87], v[166:169], v[204:207], v[84:87]
	v_mfma_f32_16x16x32_bf16 v[80:83], v[180:183], v[204:207], v[80:83]
	v_mfma_f32_16x16x32_bf16 v[68:71], v[166:169], v[212:215], v[68:71]
	v_mfma_f32_16x16x32_bf16 v[64:67], v[180:183], v[212:215], v[64:67]
	s_barrier
	s_add_i32 s8, s89, s43
	v_lshl_add_u64 v[216:217], v[216:217], 0, s[72:73]
	s_mov_b32 m0, s8
	ds_read_b128 v[184:187], v175 offset:49152
	ds_read_b128 v[188:191], v175 offset:50176
	ds_read_b128 v[192:195], v175 offset:51200
	ds_read_b128 v[196:199], v175 offset:52224
	ds_read_b128 v[200:203], v175 offset:53248
	ds_read_b128 v[204:207], v175 offset:54272
	ds_read_b128 v[208:211], v175 offset:55296
	ds_read_b128 v[212:215], v175 offset:56320
	global_load_lds_dwordx4 v[216:217], off
	s_add_i32 m0, s8, 0x2000
	s_add_u32 s6, s6, 0x80080
	v_lshl_add_u64 v[216:217], v[218:219], 0, s[72:73]
	s_addc_u32 s7, s7, 0
	s_add_i32 s8, s90, s43
	global_load_lds_dwordx4 v[216:217], off
	v_lshl_add_u64 v[216:217], s[6:7], 0, v[144:145]
	s_mov_b32 m0, s8
	s_nop 0
	global_load_lds_dwordx4 v[216:217], off
	v_lshl_add_u64 v[216:217], s[6:7], 0, v[146:147]
	s_add_i32 m0, s8, 0x2000
	s_nop 0
	global_load_lds_dwordx4 v[216:217], off
	v_lshl_add_u64 v[216:217], v[220:221], 0, s[72:73]
	s_mov_b32 m0, s49
	s_nop 0
	global_load_lds_dwordx4 v[216:217], off
	v_lshl_add_u64 v[216:217], v[222:223], 0, s[72:73]
	s_mov_b32 m0, s50
	s_nop 0
	global_load_lds_dwordx4 v[216:217], off
	s_waitcnt vmcnt(8)
	s_waitcnt lgkmcnt(0)
	s_barrier
	s_waitcnt lgkmcnt(0)
	v_mfma_f32_16x16x32_bf16 v[60:63], v[128:131], v[184:187], v[60:63]
	v_mfma_f32_16x16x32_bf16 v[56:59], v[136:139], v[184:187], v[56:59]
	v_mfma_f32_16x16x32_bf16 v[44:47], v[128:131], v[192:195], v[44:47]
	v_mfma_f32_16x16x32_bf16 v[40:43], v[136:139], v[192:195], v[40:43]
	v_mfma_f32_16x16x32_bf16 v[28:31], v[128:131], v[200:203], v[28:31]
	v_mfma_f32_16x16x32_bf16 v[24:27], v[136:139], v[200:203], v[24:27]
	v_mfma_f32_16x16x32_bf16 v[12:15], v[128:131], v[208:211], v[12:15]
	v_mfma_f32_16x16x32_bf16 v[8:11], v[136:139], v[208:211], v[8:11]
	v_mfma_f32_16x16x32_bf16 v[60:63], v[132:135], v[188:191], v[60:63]
	v_mfma_f32_16x16x32_bf16 v[56:59], v[140:143], v[188:191], v[56:59]
	v_mfma_f32_16x16x32_bf16 v[44:47], v[132:135], v[196:199], v[44:47]
	v_mfma_f32_16x16x32_bf16 v[40:43], v[140:143], v[196:199], v[40:43]
	v_mfma_f32_16x16x32_bf16 v[28:31], v[132:135], v[204:207], v[28:31]
	v_mfma_f32_16x16x32_bf16 v[24:27], v[140:143], v[204:207], v[24:27]
	v_mfma_f32_16x16x32_bf16 v[12:15], v[132:135], v[212:215], v[12:15]
	v_mfma_f32_16x16x32_bf16 v[8:11], v[140:143], v[212:215], v[8:11]
	v_mfma_f32_16x16x32_bf16 v[52:55], v[162:165], v[184:187], v[52:55]
	v_mfma_f32_16x16x32_bf16 v[48:51], v[176:179], v[184:187], v[48:51]
	v_mfma_f32_16x16x32_bf16 v[36:39], v[162:165], v[192:195], v[36:39]
	v_mfma_f32_16x16x32_bf16 v[32:35], v[176:179], v[192:195], v[32:35]
	v_mfma_f32_16x16x32_bf16 v[20:23], v[162:165], v[200:203], v[20:23]
	v_mfma_f32_16x16x32_bf16 v[16:19], v[176:179], v[200:203], v[16:19]
	v_mfma_f32_16x16x32_bf16 v[4:7], v[162:165], v[208:211], v[4:7]
	v_mfma_f32_16x16x32_bf16 v[0:3], v[176:179], v[208:211], v[0:3]
	v_mfma_f32_16x16x32_bf16 v[52:55], v[166:169], v[188:191], v[52:55]
	v_mfma_f32_16x16x32_bf16 v[48:51], v[180:183], v[188:191], v[48:51]
	v_mfma_f32_16x16x32_bf16 v[36:39], v[166:169], v[196:199], v[36:39]
	v_mfma_f32_16x16x32_bf16 v[32:35], v[180:183], v[196:199], v[32:35]
	v_mfma_f32_16x16x32_bf16 v[20:23], v[166:169], v[204:207], v[20:23]
	v_mfma_f32_16x16x32_bf16 v[16:19], v[180:183], v[204:207], v[16:19]
	v_mfma_f32_16x16x32_bf16 v[4:7], v[166:169], v[212:215], v[4:7]
	v_mfma_f32_16x16x32_bf16 v[0:3], v[180:183], v[212:215], v[0:3]
	s_barrier
	s_add_i32 s85, s85, 2
	s_add_u32 s4, s4, 0x100
	s_addc_u32 s5, s5, 0
	s_add_u32 s77, s77, 0x100
	s_addc_u32 s84, s84, 0
	s_cmp_gt_u32 s85, 29
	s_cbranch_scc0 .LBB0_468
	s_and_b64 vcc, exec, s[74:75]
	s_cbranch_vccz .LBB0_471
	s_barrier

.LBB0_797:
	ds_read_b128 v[152:155], v146
	ds_read_b128 v[156:159], v146 offset:1024
	ds_read_b128 v[160:163], v146 offset:2048
	ds_read_b128 v[164:167], v146 offset:3072
	ds_read_b128 v[168:171], v147
	ds_read_b128 v[172:175], v147 offset:1024
	ds_read_b128 v[176:179], v147 offset:2048
	ds_read_b128 v[180:183], v147 offset:3072
	s_add_u32 s22, s20, 0xf8980080
	s_addc_u32 s23, s21, -1
	s_cmp_lg_u32 s46, 28
	s_cselect_b32 s22, s22, 0
	s_cselect_b32 s23, s23, 0
	s_add_u32 s24, s12, s22
	s_addc_u32 s25, s13, s23
	s_add_u32 s22, s6, s22
	s_addc_u32 s23, s7, s23
	s_mov_b32 m0, s47
	v_lshl_add_u64 v[216:217], v[138:139], 0, s[20:21]
	ds_read_b128 v[184:187], v148
	ds_read_b128 v[188:191], v148 offset:1024
	ds_read_b128 v[192:195], v148 offset:2048
	ds_read_b128 v[196:199], v148 offset:3072
	ds_read_b128 v[200:203], v148 offset:4096
	ds_read_b128 v[204:207], v148 offset:5120
	ds_read_b128 v[208:211], v148 offset:6144
	ds_read_b128 v[212:215], v148 offset:7168
	global_load_lds_dwordx4 v[216:217], off
	v_lshl_add_u64 v[216:217], v[140:141], 0, s[20:21]
	s_mov_b32 m0, s48
	s_nop 0
	global_load_lds_dwordx4 v[216:217], off
	s_waitcnt vmcnt(8)
	s_waitcnt lgkmcnt(0)
	s_barrier
	s_waitcnt lgkmcnt(0)
	v_mfma_f32_16x16x32_bf16 v[124:127], v[152:155], v[184:187], v[124:127]
	v_mfma_f32_16x16x32_bf16 v[120:123], v[160:163], v[184:187], v[120:123]
	v_mfma_f32_16x16x32_bf16 v[108:111], v[152:155], v[192:195], v[108:111]
	v_mfma_f32_16x16x32_bf16 v[104:107], v[160:163], v[192:195], v[104:107]
	v_mfma_f32_16x16x32_bf16 v[92:95], v[152:155], v[200:203], v[92:95]
	v_mfma_f32_16x16x32_bf16 v[88:91], v[160:163], v[200:203], v[88:91]
	v_mfma_f32_16x16x32_bf16 v[76:79], v[152:155], v[208:211], v[76:79]
	v_mfma_f32_16x16x32_bf16 v[72:75], v[160:163], v[208:211], v[72:75]
	v_mfma_f32_16x16x32_bf16 v[124:127], v[156:159], v[188:191], v[124:127]
	v_mfma_f32_16x16x32_bf16 v[120:123], v[164:167], v[188:191], v[120:123]
	v_mfma_f32_16x16x32_bf16 v[108:111], v[156:159], v[196:199], v[108:111]
	v_mfma_f32_16x16x32_bf16 v[104:107], v[164:167], v[196:199], v[104:107]
	v_mfma_f32_16x16x32_bf16 v[92:95], v[156:159], v[204:207], v[92:95]
	v_mfma_f32_16x16x32_bf16 v[88:91], v[164:167], v[204:207], v[88:91]
	v_mfma_f32_16x16x32_bf16 v[76:79], v[156:159], v[212:215], v[76:79]
	v_mfma_f32_16x16x32_bf16 v[72:75], v[164:167], v[212:215], v[72:75]
	v_mfma_f32_16x16x32_bf16 v[116:119], v[168:171], v[184:187], v[116:119]
	v_mfma_f32_16x16x32_bf16 v[112:115], v[176:179], v[184:187], v[112:115]
	v_mfma_f32_16x16x32_bf16 v[100:103], v[168:171], v[192:195], v[100:103]
	v_mfma_f32_16x16x32_bf16 v[96:99], v[176:179], v[192:195], v[96:99]
	v_mfma_f32_16x16x32_bf16 v[84:87], v[168:171], v[200:203], v[84:87]
	v_mfma_f32_16x16x32_bf16 v[80:83], v[176:179], v[200:203], v[80:83]
	v_mfma_f32_16x16x32_bf16 v[68:71], v[168:171], v[208:211], v[68:71]
	v_mfma_f32_16x16x32_bf16 v[64:67], v[176:179], v[208:211], v[64:67]
	v_mfma_f32_16x16x32_bf16 v[116:119], v[172:175], v[188:191], v[116:119]
	v_mfma_f32_16x16x32_bf16 v[112:115], v[180:183], v[188:191], v[112:115]
	v_mfma_f32_16x16x32_bf16 v[100:103], v[172:175], v[196:199], v[100:103]
	v_mfma_f32_16x16x32_bf16 v[96:99], v[180:183], v[196:199], v[96:99]
	v_mfma_f32_16x16x32_bf16 v[84:87], v[172:175], v[204:207], v[84:87]
	v_mfma_f32_16x16x32_bf16 v[80:83], v[180:183], v[204:207], v[80:83]
	v_mfma_f32_16x16x32_bf16 v[68:71], v[172:175], v[212:215], v[68:71]
	v_mfma_f32_16x16x32_bf16 v[64:67], v[180:183], v[212:215], v[64:67]
	s_barrier
	s_mov_b32 m0, s49
	v_lshl_add_u64 v[216:217], s[22:23], 0, v[128:129]
	s_add_u32 s86, s22, 0x80000
	ds_read_b128 v[184:187], v148 offset:16384
	ds_read_b128 v[188:191], v148 offset:17408
	ds_read_b128 v[192:195], v148 offset:18432
	ds_read_b128 v[196:199], v148 offset:19456
	ds_read_b128 v[200:203], v148 offset:20480
	ds_read_b128 v[204:207], v148 offset:21504
	ds_read_b128 v[208:211], v148 offset:22528
	ds_read_b128 v[212:215], v148 offset:23552
	global_load_lds_dwordx4 v[216:217], off
	v_lshl_add_u64 v[218:219], s[22:23], 0, v[130:131]
	s_mov_b32 m0, s50
	s_addc_u32 s87, s23, 0
	global_load_lds_dwordx4 v[218:219], off
	v_lshl_add_u64 v[220:221], s[86:87], 0, v[128:129]
	s_mov_b32 m0, s51
	v_lshl_add_u64 v[222:223], s[24:25], 0, v[130:131]
	global_load_lds_dwordx4 v[220:221], off
	v_lshl_add_u64 v[220:221], s[86:87], 0, v[130:131]
	s_mov_b32 m0, s56
	s_nop 0
	global_load_lds_dwordx4 v[220:221], off
	v_lshl_add_u64 v[220:221], s[24:25], 0, v[128:129]
	s_mov_b32 m0, s5
	s_nop 0
	global_load_lds_dwordx4 v[220:221], off
	s_mov_b32 m0, s39
	s_nop 0
	global_load_lds_dwordx4 v[222:223], off
	s_waitcnt vmcnt(8)
	s_waitcnt lgkmcnt(0)
	s_barrier
	s_waitcnt lgkmcnt(0)
	v_mfma_f32_16x16x32_bf16 v[60:63], v[152:155], v[184:187], v[60:63]
	v_mfma_f32_16x16x32_bf16 v[56:59], v[160:163], v[184:187], v[56:59]
	v_mfma_f32_16x16x32_bf16 v[44:47], v[152:155], v[192:195], v[44:47]
	v_mfma_f32_16x16x32_bf16 v[40:43], v[160:163], v[192:195], v[40:43]
	v_mfma_f32_16x16x32_bf16 v[28:31], v[152:155], v[200:203], v[28:31]
	v_mfma_f32_16x16x32_bf16 v[24:27], v[160:163], v[200:203], v[24:27]
	v_mfma_f32_16x16x32_bf16 v[12:15], v[152:155], v[208:211], v[12:15]
	v_mfma_f32_16x16x32_bf16 v[8:11], v[160:163], v[208:211], v[8:11]
	v_mfma_f32_16x16x32_bf16 v[60:63], v[156:159], v[188:191], v[60:63]
	v_mfma_f32_16x16x32_bf16 v[56:59], v[164:167], v[188:191], v[56:59]
	v_mfma_f32_16x16x32_bf16 v[44:47], v[156:159], v[196:199], v[44:47]
	v_mfma_f32_16x16x32_bf16 v[40:43], v[164:167], v[196:199], v[40:43]
	v_mfma_f32_16x16x32_bf16 v[28:31], v[156:159], v[204:207], v[28:31]
	v_mfma_f32_16x16x32_bf16 v[24:27], v[164:167], v[204:207], v[24:27]
	v_mfma_f32_16x16x32_bf16 v[12:15], v[156:159], v[212:215], v[12:15]
	v_mfma_f32_16x16x32_bf16 v[8:11], v[164:167], v[212:215], v[8:11]
	v_mfma_f32_16x16x32_bf16 v[52:55], v[168:171], v[184:187], v[52:55]
	v_mfma_f32_16x16x32_bf16 v[48:51], v[176:179], v[184:187], v[48:51]
	v_mfma_f32_16x16x32_bf16 v[36:39], v[168:171], v[192:195], v[36:39]
	v_mfma_f32_16x16x32_bf16 v[32:35], v[176:179], v[192:195], v[32:35]
	v_mfma_f32_16x16x32_bf16 v[20:23], v[168:171], v[200:203], v[20:23]
	v_mfma_f32_16x16x32_bf16 v[16:19], v[176:179], v[200:203], v[16:19]
	v_mfma_f32_16x16x32_bf16 v[4:7], v[168:171], v[208:211], v[4:7]
	v_mfma_f32_16x16x32_bf16 v[0:3], v[176:179], v[208:211], v[0:3]
	v_mfma_f32_16x16x32_bf16 v[52:55], v[172:175], v[188:191], v[52:55]
	v_mfma_f32_16x16x32_bf16 v[48:51], v[180:183], v[188:191], v[48:51]
	v_mfma_f32_16x16x32_bf16 v[36:39], v[172:175], v[196:199], v[36:39]
	v_mfma_f32_16x16x32_bf16 v[32:35], v[180:183], v[196:199], v[32:35]
	v_mfma_f32_16x16x32_bf16 v[20:23], v[172:175], v[204:207], v[20:23]
	v_mfma_f32_16x16x32_bf16 v[16:19], v[180:183], v[204:207], v[16:19]
	v_mfma_f32_16x16x32_bf16 v[4:7], v[172:175], v[212:215], v[4:7]
	v_mfma_f32_16x16x32_bf16 v[0:3], v[180:183], v[212:215], v[0:3]
	s_barrier
	ds_read_b128 v[152:155], v149
	ds_read_b128 v[156:159], v149 offset:1024
	ds_read_b128 v[160:163], v149 offset:2048
	ds_read_b128 v[164:167], v149 offset:3072
	ds_read_b128 v[168:171], v150
	ds_read_b128 v[172:175], v150 offset:1024
	ds_read_b128 v[176:179], v150 offset:2048
	ds_read_b128 v[180:183], v150 offset:3072
	s_add_u32 s24, s24, 0x80000
	s_addc_u32 s25, s25, 0
	s_mov_b32 m0, s40
	v_lshl_add_u64 v[224:225], s[24:25], 0, v[128:129]
	ds_read_b128 v[184:187], v148 offset:32768
	ds_read_b128 v[188:191], v148 offset:33792
	ds_read_b128 v[192:195], v148 offset:34816
	ds_read_b128 v[196:199], v148 offset:35840
	ds_read_b128 v[200:203], v148 offset:36864
	ds_read_b128 v[204:207], v148 offset:37888
	ds_read_b128 v[208:211], v148 offset:38912
	ds_read_b128 v[212:215], v148 offset:39936
	global_load_lds_dwordx4 v[224:225], off
	v_lshl_add_u64 v[224:225], s[24:25], 0, v[130:131]
	s_mov_b32 m0, s42
	s_nop 0
	global_load_lds_dwordx4 v[224:225], off
	s_waitcnt vmcnt(8)
	s_waitcnt lgkmcnt(0)
	s_barrier
	s_waitcnt lgkmcnt(0)
	v_mfma_f32_16x16x32_bf16 v[124:127], v[152:155], v[184:187], v[124:127]
	v_mfma_f32_16x16x32_bf16 v[120:123], v[160:163], v[184:187], v[120:123]
	v_mfma_f32_16x16x32_bf16 v[108:111], v[152:155], v[192:195], v[108:111]
	v_mfma_f32_16x16x32_bf16 v[104:107], v[160:163], v[192:195], v[104:107]
	v_mfma_f32_16x16x32_bf16 v[92:95], v[152:155], v[200:203], v[92:95]
	v_mfma_f32_16x16x32_bf16 v[88:91], v[160:163], v[200:203], v[88:91]
	v_mfma_f32_16x16x32_bf16 v[76:79], v[152:155], v[208:211], v[76:79]
	v_mfma_f32_16x16x32_bf16 v[72:75], v[160:163], v[208:211], v[72:75]
	v_mfma_f32_16x16x32_bf16 v[124:127], v[156:159], v[188:191], v[124:127]
	v_mfma_f32_16x16x32_bf16 v[120:123], v[164:167], v[188:191], v[120:123]
	v_mfma_f32_16x16x32_bf16 v[108:111], v[156:159], v[196:199], v[108:111]
	v_mfma_f32_16x16x32_bf16 v[104:107], v[164:167], v[196:199], v[104:107]
	v_mfma_f32_16x16x32_bf16 v[92:95], v[156:159], v[204:207], v[92:95]
	v_mfma_f32_16x16x32_bf16 v[88:91], v[164:167], v[204:207], v[88:91]
	v_mfma_f32_16x16x32_bf16 v[76:79], v[156:159], v[212:215], v[76:79]
	v_mfma_f32_16x16x32_bf16 v[72:75], v[164:167], v[212:215], v[72:75]
	v_mfma_f32_16x16x32_bf16 v[116:119], v[168:171], v[184:187], v[116:119]
	v_mfma_f32_16x16x32_bf16 v[112:115], v[176:179], v[184:187], v[112:115]
	v_mfma_f32_16x16x32_bf16 v[100:103], v[168:171], v[192:195], v[100:103]
	v_mfma_f32_16x16x32_bf16 v[96:99], v[176:179], v[192:195], v[96:99]
	v_mfma_f32_16x16x32_bf16 v[84:87], v[168:171], v[200:203], v[84:87]
	v_mfma_f32_16x16x32_bf16 v[80:83], v[176:179], v[200:203], v[80:83]
	v_mfma_f32_16x16x32_bf16 v[68:71], v[168:171], v[208:211], v[68:71]
	v_mfma_f32_16x16x32_bf16 v[64:67], v[176:179], v[208:211], v[64:67]
	v_mfma_f32_16x16x32_bf16 v[116:119], v[172:175], v[188:191], v[116:119]
	v_mfma_f32_16x16x32_bf16 v[112:115], v[180:183], v[188:191], v[112:115]
	v_mfma_f32_16x16x32_bf16 v[100:103], v[172:175], v[196:199], v[100:103]
	v_mfma_f32_16x16x32_bf16 v[96:99], v[180:183], v[196:199], v[96:99]
	v_mfma_f32_16x16x32_bf16 v[84:87], v[172:175], v[204:207], v[84:87]
	v_mfma_f32_16x16x32_bf16 v[80:83], v[180:183], v[204:207], v[80:83]
	v_mfma_f32_16x16x32_bf16 v[68:71], v[172:175], v[212:215], v[68:71]
	v_mfma_f32_16x16x32_bf16 v[64:67], v[180:183], v[212:215], v[64:67]
	s_barrier
	s_mov_b32 m0, s57
	v_lshl_add_u64 v[216:217], v[216:217], 0, s[2:3]
	s_add_u32 s22, s22, 0x80080
	ds_read_b128 v[184:187], v148 offset:49152
	ds_read_b128 v[188:191], v148 offset:50176
	ds_read_b128 v[192:195], v148 offset:51200
	ds_read_b128 v[196:199], v148 offset:52224
	ds_read_b128 v[200:203], v148 offset:53248
	ds_read_b128 v[204:207], v148 offset:54272
	ds_read_b128 v[208:211], v148 offset:55296
	ds_read_b128 v[212:215], v148 offset:56320
	global_load_lds_dwordx4 v[216:217], off
	v_lshl_add_u64 v[216:217], v[218:219], 0, s[2:3]
	s_mov_b32 m0, s58
	s_addc_u32 s23, s23, 0
	global_load_lds_dwordx4 v[216:217], off
	v_lshl_add_u64 v[216:217], s[22:23], 0, v[128:129]
	s_mov_b32 m0, s59
	s_nop 0
	global_load_lds_dwordx4 v[216:217], off
	v_lshl_add_u64 v[216:217], s[22:23], 0, v[130:131]
	s_mov_b32 m0, s84
	s_nop 0
	global_load_lds_dwordx4 v[216:217], off
	v_lshl_add_u64 v[216:217], v[220:221], 0, s[2:3]
	s_mov_b32 m0, s44
	s_nop 0
	global_load_lds_dwordx4 v[216:217], off
	v_lshl_add_u64 v[216:217], v[222:223], 0, s[2:3]
	s_mov_b32 m0, s45
	s_nop 0
	global_load_lds_dwordx4 v[216:217], off
	s_waitcnt vmcnt(8)
	s_waitcnt lgkmcnt(0)
	s_barrier
	s_waitcnt lgkmcnt(0)
	v_mfma_f32_16x16x32_bf16 v[60:63], v[152:155], v[184:187], v[60:63]
	v_mfma_f32_16x16x32_bf16 v[56:59], v[160:163], v[184:187], v[56:59]
	v_mfma_f32_16x16x32_bf16 v[44:47], v[152:155], v[192:195], v[44:47]
	v_mfma_f32_16x16x32_bf16 v[40:43], v[160:163], v[192:195], v[40:43]
	v_mfma_f32_16x16x32_bf16 v[28:31], v[152:155], v[200:203], v[28:31]
	v_mfma_f32_16x16x32_bf16 v[24:27], v[160:163], v[200:203], v[24:27]
	v_mfma_f32_16x16x32_bf16 v[12:15], v[152:155], v[208:211], v[12:15]
	v_mfma_f32_16x16x32_bf16 v[8:11], v[160:163], v[208:211], v[8:11]
	v_mfma_f32_16x16x32_bf16 v[60:63], v[156:159], v[188:191], v[60:63]
	v_mfma_f32_16x16x32_bf16 v[56:59], v[164:167], v[188:191], v[56:59]
	v_mfma_f32_16x16x32_bf16 v[44:47], v[156:159], v[196:199], v[44:47]
	v_mfma_f32_16x16x32_bf16 v[40:43], v[164:167], v[196:199], v[40:43]
	v_mfma_f32_16x16x32_bf16 v[28:31], v[156:159], v[204:207], v[28:31]
	v_mfma_f32_16x16x32_bf16 v[24:27], v[164:167], v[204:207], v[24:27]
	v_mfma_f32_16x16x32_bf16 v[12:15], v[156:159], v[212:215], v[12:15]
	v_mfma_f32_16x16x32_bf16 v[8:11], v[164:167], v[212:215], v[8:11]
	v_mfma_f32_16x16x32_bf16 v[52:55], v[168:171], v[184:187], v[52:55]
	v_mfma_f32_16x16x32_bf16 v[48:51], v[176:179], v[184:187], v[48:51]
	v_mfma_f32_16x16x32_bf16 v[36:39], v[168:171], v[192:195], v[36:39]
	v_mfma_f32_16x16x32_bf16 v[32:35], v[176:179], v[192:195], v[32:35]
	v_mfma_f32_16x16x32_bf16 v[20:23], v[168:171], v[200:203], v[20:23]
	v_mfma_f32_16x16x32_bf16 v[16:19], v[176:179], v[200:203], v[16:19]
	v_mfma_f32_16x16x32_bf16 v[4:7], v[168:171], v[208:211], v[4:7]
	v_mfma_f32_16x16x32_bf16 v[0:3], v[176:179], v[208:211], v[0:3]
	v_mfma_f32_16x16x32_bf16 v[52:55], v[172:175], v[188:191], v[52:55]
	v_mfma_f32_16x16x32_bf16 v[48:51], v[180:183], v[188:191], v[48:51]
	v_mfma_f32_16x16x32_bf16 v[36:39], v[172:175], v[196:199], v[36:39]
	v_mfma_f32_16x16x32_bf16 v[32:35], v[180:183], v[196:199], v[32:35]
	v_mfma_f32_16x16x32_bf16 v[20:23], v[172:175], v[204:207], v[20:23]
	v_mfma_f32_16x16x32_bf16 v[16:19], v[180:183], v[204:207], v[16:19]
	v_mfma_f32_16x16x32_bf16 v[4:7], v[172:175], v[212:215], v[4:7]
	v_mfma_f32_16x16x32_bf16 v[0:3], v[180:183], v[212:215], v[0:3]
	s_barrier
	s_add_i32 s46, s46, 2
	s_add_u32 s20, s20, 0x100
	s_addc_u32 s21, s21, 0
	s_cmp_gt_u32 s46, 29
	s_cbranch_scc0 .LBB0_797
	s_cmpk_lt_u32 s38, 0x100
	s_cbranch_scc0 .LBB0_800
	s_barrier

.LBB0_1058:
	ds_read_b128 v[136:139], v143
	ds_read_b128 v[146:149], v143 offset:1024
	ds_read_b128 v[150:153], v143 offset:2048
	ds_read_b128 v[154:157], v143 offset:3072
	ds_read_b128 v[158:161], v144
	ds_read_b128 v[162:165], v144 offset:1024
	ds_read_b128 v[166:169], v144 offset:2048
	ds_read_b128 v[170:173], v144 offset:3072
	s_add_u32 s26, s24, 0xfffc0080
	s_addc_u32 s27, s25, -1
	s_cmp_eq_u32 s56, 12
	s_cselect_b32 s29, s46, s27
	s_cselect_b32 s28, s47, s26
	s_cselect_b32 s27, s48, s51
	s_cselect_b32 s26, s49, s50
	v_lshl_add_u64 v[206:207], s[24:25], 0, v[132:133]
	s_add_i32 m0, s35, 0xc000
	ds_read_b128 v[174:177], v145
	ds_read_b128 v[178:181], v145 offset:1024
	ds_read_b128 v[182:185], v145 offset:2048
	ds_read_b128 v[186:189], v145 offset:3072
	ds_read_b128 v[190:193], v145 offset:4096
	ds_read_b128 v[194:197], v145 offset:5120
	ds_read_b128 v[198:201], v145 offset:6144
	ds_read_b128 v[202:205], v145 offset:7168
	global_load_lds_dwordx4 v[206:207], off
	v_lshl_add_u64 v[206:207], s[24:25], 0, v[134:135]
	s_add_i32 m0, s35, 0xe000
	s_nop 0
	global_load_lds_dwordx4 v[206:207], off
	s_waitcnt vmcnt(8)
	s_waitcnt lgkmcnt(0)
	s_barrier
	s_waitcnt lgkmcnt(0)
	v_mfma_f32_16x16x32_bf16 v[124:127], v[136:139], v[174:177], v[124:127]
	v_mfma_f32_16x16x32_bf16 v[120:123], v[150:153], v[174:177], v[120:123]
	v_mfma_f32_16x16x32_bf16 v[108:111], v[136:139], v[182:185], v[108:111]
	v_mfma_f32_16x16x32_bf16 v[104:107], v[150:153], v[182:185], v[104:107]
	v_mfma_f32_16x16x32_bf16 v[92:95], v[136:139], v[190:193], v[92:95]
	v_mfma_f32_16x16x32_bf16 v[88:91], v[150:153], v[190:193], v[88:91]
	v_mfma_f32_16x16x32_bf16 v[76:79], v[136:139], v[198:201], v[76:79]
	v_mfma_f32_16x16x32_bf16 v[72:75], v[150:153], v[198:201], v[72:75]
	v_mfma_f32_16x16x32_bf16 v[124:127], v[146:149], v[178:181], v[124:127]
	v_mfma_f32_16x16x32_bf16 v[120:123], v[154:157], v[178:181], v[120:123]
	v_mfma_f32_16x16x32_bf16 v[108:111], v[146:149], v[186:189], v[108:111]
	v_mfma_f32_16x16x32_bf16 v[104:107], v[154:157], v[186:189], v[104:107]
	v_mfma_f32_16x16x32_bf16 v[92:95], v[146:149], v[194:197], v[92:95]
	v_mfma_f32_16x16x32_bf16 v[88:91], v[154:157], v[194:197], v[88:91]
	v_mfma_f32_16x16x32_bf16 v[76:79], v[146:149], v[202:205], v[76:79]
	v_mfma_f32_16x16x32_bf16 v[72:75], v[154:157], v[202:205], v[72:75]
	v_mfma_f32_16x16x32_bf16 v[116:119], v[158:161], v[174:177], v[116:119]
	v_mfma_f32_16x16x32_bf16 v[112:115], v[166:169], v[174:177], v[112:115]
	v_mfma_f32_16x16x32_bf16 v[100:103], v[158:161], v[182:185], v[100:103]
	v_mfma_f32_16x16x32_bf16 v[96:99], v[166:169], v[182:185], v[96:99]
	v_mfma_f32_16x16x32_bf16 v[84:87], v[158:161], v[190:193], v[84:87]
	v_mfma_f32_16x16x32_bf16 v[80:83], v[166:169], v[190:193], v[80:83]
	v_mfma_f32_16x16x32_bf16 v[68:71], v[158:161], v[198:201], v[68:71]
	v_mfma_f32_16x16x32_bf16 v[64:67], v[166:169], v[198:201], v[64:67]
	v_mfma_f32_16x16x32_bf16 v[116:119], v[162:165], v[178:181], v[116:119]
	v_mfma_f32_16x16x32_bf16 v[112:115], v[170:173], v[178:181], v[112:115]
	v_mfma_f32_16x16x32_bf16 v[100:103], v[162:165], v[186:189], v[100:103]
	v_mfma_f32_16x16x32_bf16 v[96:99], v[170:173], v[186:189], v[96:99]
	v_mfma_f32_16x16x32_bf16 v[84:87], v[162:165], v[194:197], v[84:87]
	v_mfma_f32_16x16x32_bf16 v[80:83], v[170:173], v[194:197], v[80:83]
	v_mfma_f32_16x16x32_bf16 v[68:71], v[162:165], v[202:205], v[68:71]
	v_mfma_f32_16x16x32_bf16 v[64:67], v[170:173], v[202:205], v[64:67]
	s_barrier
	s_add_i32 s57, s42, s33
	v_lshl_add_u64 v[206:207], s[26:27], 0, v[130:131]
	s_mov_b32 m0, s57
	ds_read_b128 v[174:177], v145 offset:16384
	ds_read_b128 v[178:181], v145 offset:17408
	ds_read_b128 v[182:185], v145 offset:18432
	ds_read_b128 v[186:189], v145 offset:19456
	ds_read_b128 v[190:193], v145 offset:20480
	ds_read_b128 v[194:197], v145 offset:21504
	ds_read_b128 v[198:201], v145 offset:22528
	ds_read_b128 v[202:205], v145 offset:23552
	global_load_lds_dwordx4 v[206:207], off
	s_add_i32 m0, s57, 0x2000
	s_add_u32 s58, s26, 0x40000
	v_lshl_add_u64 v[208:209], s[26:27], 0, v[128:129]
	s_addc_u32 s59, s27, 0
	s_add_i32 s57, s43, s33
	global_load_lds_dwordx4 v[208:209], off
	v_lshl_add_u64 v[210:211], s[58:59], 0, v[130:131]
	s_mov_b32 m0, s57
	v_lshl_add_u64 v[212:213], s[28:29], 0, v[128:129]
	global_load_lds_dwordx4 v[210:211], off
	v_lshl_add_u64 v[210:211], s[58:59], 0, v[128:129]
	s_add_i32 m0, s57, 0x2000
	s_nop 0
	global_load_lds_dwordx4 v[210:211], off
	v_lshl_add_u64 v[210:211], s[28:29], 0, v[130:131]
	s_mov_b32 m0, s35
	s_nop 0
	global_load_lds_dwordx4 v[210:211], off
	s_mov_b32 m0, s36
	s_nop 0
	global_load_lds_dwordx4 v[212:213], off
	s_waitcnt vmcnt(8)
	s_waitcnt lgkmcnt(0)
	s_barrier
	s_waitcnt lgkmcnt(0)
	v_mfma_f32_16x16x32_bf16 v[60:63], v[136:139], v[174:177], v[60:63]
	v_mfma_f32_16x16x32_bf16 v[56:59], v[150:153], v[174:177], v[56:59]
	v_mfma_f32_16x16x32_bf16 v[44:47], v[136:139], v[182:185], v[44:47]
	v_mfma_f32_16x16x32_bf16 v[40:43], v[150:153], v[182:185], v[40:43]
	v_mfma_f32_16x16x32_bf16 v[28:31], v[136:139], v[190:193], v[28:31]
	v_mfma_f32_16x16x32_bf16 v[24:27], v[150:153], v[190:193], v[24:27]
	v_mfma_f32_16x16x32_bf16 v[12:15], v[136:139], v[198:201], v[12:15]
	v_mfma_f32_16x16x32_bf16 v[8:11], v[150:153], v[198:201], v[8:11]
	v_mfma_f32_16x16x32_bf16 v[60:63], v[146:149], v[178:181], v[60:63]
	v_mfma_f32_16x16x32_bf16 v[56:59], v[154:157], v[178:181], v[56:59]
	v_mfma_f32_16x16x32_bf16 v[44:47], v[146:149], v[186:189], v[44:47]
	v_mfma_f32_16x16x32_bf16 v[40:43], v[154:157], v[186:189], v[40:43]
	v_mfma_f32_16x16x32_bf16 v[28:31], v[146:149], v[194:197], v[28:31]
	v_mfma_f32_16x16x32_bf16 v[24:27], v[154:157], v[194:197], v[24:27]
	v_mfma_f32_16x16x32_bf16 v[12:15], v[146:149], v[202:205], v[12:15]
	v_mfma_f32_16x16x32_bf16 v[8:11], v[154:157], v[202:205], v[8:11]
	v_mfma_f32_16x16x32_bf16 v[52:55], v[158:161], v[174:177], v[52:55]
	v_mfma_f32_16x16x32_bf16 v[48:51], v[166:169], v[174:177], v[48:51]
	v_mfma_f32_16x16x32_bf16 v[36:39], v[158:161], v[182:185], v[36:39]
	v_mfma_f32_16x16x32_bf16 v[32:35], v[166:169], v[182:185], v[32:35]
	v_mfma_f32_16x16x32_bf16 v[20:23], v[158:161], v[190:193], v[20:23]
	v_mfma_f32_16x16x32_bf16 v[16:19], v[166:169], v[190:193], v[16:19]
	v_mfma_f32_16x16x32_bf16 v[4:7], v[158:161], v[198:201], v[4:7]
	v_mfma_f32_16x16x32_bf16 v[0:3], v[166:169], v[198:201], v[0:3]
	v_mfma_f32_16x16x32_bf16 v[52:55], v[162:165], v[178:181], v[52:55]
	v_mfma_f32_16x16x32_bf16 v[48:51], v[170:173], v[178:181], v[48:51]
	v_mfma_f32_16x16x32_bf16 v[36:39], v[162:165], v[186:189], v[36:39]
	v_mfma_f32_16x16x32_bf16 v[32:35], v[170:173], v[186:189], v[32:35]
	v_mfma_f32_16x16x32_bf16 v[20:23], v[162:165], v[194:197], v[20:23]
	v_mfma_f32_16x16x32_bf16 v[16:19], v[170:173], v[194:197], v[16:19]
	v_mfma_f32_16x16x32_bf16 v[4:7], v[162:165], v[202:205], v[4:7]
	v_mfma_f32_16x16x32_bf16 v[0:3], v[170:173], v[202:205], v[0:3]
	s_barrier
	s_add_i32 s57, 0, 0x18000
	s_add_i32 s58, 0, 0x1c000
	v_add_u32_e32 v154, s57, v141
	v_add_u32_e32 v170, s58, v141
	ds_read_b128 v[136:139], v154
	ds_read_b128 v[146:149], v154 offset:1024
	ds_read_b128 v[150:153], v154 offset:2048
	ds_read_b128 v[154:157], v154 offset:3072
	ds_read_b128 v[158:161], v170
	ds_read_b128 v[162:165], v170 offset:1024
	ds_read_b128 v[166:169], v170 offset:2048
	ds_read_b128 v[170:173], v170 offset:3072
	s_add_u32 s28, s28, 0x40000
	s_addc_u32 s29, s29, 0
	s_mov_b32 m0, s37
	v_lshl_add_u64 v[214:215], s[28:29], 0, v[130:131]
	ds_read_b128 v[174:177], v145 offset:32768
	ds_read_b128 v[178:181], v145 offset:33792
	ds_read_b128 v[182:185], v145 offset:34816
	ds_read_b128 v[186:189], v145 offset:35840
	ds_read_b128 v[190:193], v145 offset:36864
	ds_read_b128 v[194:197], v145 offset:37888
	ds_read_b128 v[198:201], v145 offset:38912
	ds_read_b128 v[202:205], v145 offset:39936
	global_load_lds_dwordx4 v[214:215], off
	v_lshl_add_u64 v[214:215], s[28:29], 0, v[128:129]
	s_mov_b32 m0, s38
	s_nop 0
	global_load_lds_dwordx4 v[214:215], off
	s_waitcnt vmcnt(8)
	s_waitcnt lgkmcnt(0)
	s_barrier
	s_waitcnt lgkmcnt(0)
	v_mfma_f32_16x16x32_bf16 v[124:127], v[136:139], v[174:177], v[124:127]
	v_mfma_f32_16x16x32_bf16 v[120:123], v[150:153], v[174:177], v[120:123]
	v_mfma_f32_16x16x32_bf16 v[108:111], v[136:139], v[182:185], v[108:111]
	v_mfma_f32_16x16x32_bf16 v[104:107], v[150:153], v[182:185], v[104:107]
	v_mfma_f32_16x16x32_bf16 v[92:95], v[136:139], v[190:193], v[92:95]
	v_mfma_f32_16x16x32_bf16 v[88:91], v[150:153], v[190:193], v[88:91]
	v_mfma_f32_16x16x32_bf16 v[76:79], v[136:139], v[198:201], v[76:79]
	v_mfma_f32_16x16x32_bf16 v[72:75], v[150:153], v[198:201], v[72:75]
	v_mfma_f32_16x16x32_bf16 v[124:127], v[146:149], v[178:181], v[124:127]
	v_mfma_f32_16x16x32_bf16 v[120:123], v[154:157], v[178:181], v[120:123]
	v_mfma_f32_16x16x32_bf16 v[108:111], v[146:149], v[186:189], v[108:111]
	v_mfma_f32_16x16x32_bf16 v[104:107], v[154:157], v[186:189], v[104:107]
	v_mfma_f32_16x16x32_bf16 v[92:95], v[146:149], v[194:197], v[92:95]
	v_mfma_f32_16x16x32_bf16 v[88:91], v[154:157], v[194:197], v[88:91]
	v_mfma_f32_16x16x32_bf16 v[76:79], v[146:149], v[202:205], v[76:79]
	v_mfma_f32_16x16x32_bf16 v[72:75], v[154:157], v[202:205], v[72:75]
	v_mfma_f32_16x16x32_bf16 v[116:119], v[158:161], v[174:177], v[116:119]
	v_mfma_f32_16x16x32_bf16 v[112:115], v[166:169], v[174:177], v[112:115]
	v_mfma_f32_16x16x32_bf16 v[100:103], v[158:161], v[182:185], v[100:103]
	v_mfma_f32_16x16x32_bf16 v[96:99], v[166:169], v[182:185], v[96:99]
	v_mfma_f32_16x16x32_bf16 v[84:87], v[158:161], v[190:193], v[84:87]
	v_mfma_f32_16x16x32_bf16 v[80:83], v[166:169], v[190:193], v[80:83]
	v_mfma_f32_16x16x32_bf16 v[68:71], v[158:161], v[198:201], v[68:71]
	v_mfma_f32_16x16x32_bf16 v[64:67], v[166:169], v[198:201], v[64:67]
	v_mfma_f32_16x16x32_bf16 v[116:119], v[162:165], v[178:181], v[116:119]
	v_mfma_f32_16x16x32_bf16 v[112:115], v[170:173], v[178:181], v[112:115]
	v_mfma_f32_16x16x32_bf16 v[100:103], v[162:165], v[186:189], v[100:103]
	v_mfma_f32_16x16x32_bf16 v[96:99], v[170:173], v[186:189], v[96:99]
	v_mfma_f32_16x16x32_bf16 v[84:87], v[162:165], v[194:197], v[84:87]
	v_mfma_f32_16x16x32_bf16 v[80:83], v[170:173], v[194:197], v[80:83]
	v_mfma_f32_16x16x32_bf16 v[68:71], v[162:165], v[202:205], v[68:71]
	v_mfma_f32_16x16x32_bf16 v[64:67], v[170:173], v[202:205], v[64:67]
	s_barrier
	s_add_i32 s28, s57, s33
	v_lshl_add_u64 v[206:207], v[206:207], 0, s[18:19]
	s_mov_b32 m0, s28
	ds_read_b128 v[174:177], v145 offset:49152
	ds_read_b128 v[178:181], v145 offset:50176
	ds_read_b128 v[182:185], v145 offset:51200
	ds_read_b128 v[186:189], v145 offset:52224
	ds_read_b128 v[190:193], v145 offset:53248
	ds_read_b128 v[194:197], v145 offset:54272
	ds_read_b128 v[198:201], v145 offset:55296
	ds_read_b128 v[202:205], v145 offset:56320
	global_load_lds_dwordx4 v[206:207], off
	s_add_i32 m0, s28, 0x2000
	s_add_u32 s26, s26, 0x40080
	v_lshl_add_u64 v[206:207], v[208:209], 0, s[18:19]
	s_addc_u32 s27, s27, 0
	s_add_i32 s28, s58, s33
	global_load_lds_dwordx4 v[206:207], off
	v_lshl_add_u64 v[206:207], s[26:27], 0, v[130:131]
	s_mov_b32 m0, s28
	s_nop 0
	global_load_lds_dwordx4 v[206:207], off
	v_lshl_add_u64 v[206:207], s[26:27], 0, v[128:129]
	s_add_i32 m0, s28, 0x2000
	s_nop 0
	global_load_lds_dwordx4 v[206:207], off
	v_lshl_add_u64 v[206:207], v[210:211], 0, s[18:19]
	s_mov_b32 m0, s39
	s_nop 0
	global_load_lds_dwordx4 v[206:207], off
	v_lshl_add_u64 v[206:207], v[212:213], 0, s[18:19]
	s_mov_b32 m0, s40
	s_nop 0
	global_load_lds_dwordx4 v[206:207], off
	s_waitcnt vmcnt(8)
	s_waitcnt lgkmcnt(0)
	s_barrier
	s_waitcnt lgkmcnt(0)
	v_mfma_f32_16x16x32_bf16 v[60:63], v[136:139], v[174:177], v[60:63]
	v_mfma_f32_16x16x32_bf16 v[56:59], v[150:153], v[174:177], v[56:59]
	v_mfma_f32_16x16x32_bf16 v[44:47], v[136:139], v[182:185], v[44:47]
	v_mfma_f32_16x16x32_bf16 v[40:43], v[150:153], v[182:185], v[40:43]
	v_mfma_f32_16x16x32_bf16 v[28:31], v[136:139], v[190:193], v[28:31]
	v_mfma_f32_16x16x32_bf16 v[24:27], v[150:153], v[190:193], v[24:27]
	v_mfma_f32_16x16x32_bf16 v[12:15], v[136:139], v[198:201], v[12:15]
	v_mfma_f32_16x16x32_bf16 v[8:11], v[150:153], v[198:201], v[8:11]
	v_mfma_f32_16x16x32_bf16 v[60:63], v[146:149], v[178:181], v[60:63]
	v_mfma_f32_16x16x32_bf16 v[56:59], v[154:157], v[178:181], v[56:59]
	v_mfma_f32_16x16x32_bf16 v[44:47], v[146:149], v[186:189], v[44:47]
	v_mfma_f32_16x16x32_bf16 v[40:43], v[154:157], v[186:189], v[40:43]
	v_mfma_f32_16x16x32_bf16 v[28:31], v[146:149], v[194:197], v[28:31]
	v_mfma_f32_16x16x32_bf16 v[24:27], v[154:157], v[194:197], v[24:27]
	v_mfma_f32_16x16x32_bf16 v[12:15], v[146:149], v[202:205], v[12:15]
	v_mfma_f32_16x16x32_bf16 v[8:11], v[154:157], v[202:205], v[8:11]
	v_mfma_f32_16x16x32_bf16 v[52:55], v[158:161], v[174:177], v[52:55]
	v_mfma_f32_16x16x32_bf16 v[48:51], v[166:169], v[174:177], v[48:51]
	v_mfma_f32_16x16x32_bf16 v[36:39], v[158:161], v[182:185], v[36:39]
	v_mfma_f32_16x16x32_bf16 v[32:35], v[166:169], v[182:185], v[32:35]
	v_mfma_f32_16x16x32_bf16 v[20:23], v[158:161], v[190:193], v[20:23]
	v_mfma_f32_16x16x32_bf16 v[16:19], v[166:169], v[190:193], v[16:19]
	v_mfma_f32_16x16x32_bf16 v[4:7], v[158:161], v[198:201], v[4:7]
	v_mfma_f32_16x16x32_bf16 v[0:3], v[166:169], v[198:201], v[0:3]
	v_mfma_f32_16x16x32_bf16 v[52:55], v[162:165], v[178:181], v[52:55]
	v_mfma_f32_16x16x32_bf16 v[48:51], v[170:173], v[178:181], v[48:51]
	v_mfma_f32_16x16x32_bf16 v[36:39], v[162:165], v[186:189], v[36:39]
	v_mfma_f32_16x16x32_bf16 v[32:35], v[170:173], v[186:189], v[32:35]
	v_mfma_f32_16x16x32_bf16 v[20:23], v[162:165], v[194:197], v[20:23]
	v_mfma_f32_16x16x32_bf16 v[16:19], v[170:173], v[194:197], v[16:19]
	v_mfma_f32_16x16x32_bf16 v[4:7], v[162:165], v[202:205], v[4:7]
	v_mfma_f32_16x16x32_bf16 v[0:3], v[170:173], v[202:205], v[0:3]
	s_barrier
	s_add_i32 s56, s56, 2
	s_add_u32 s24, s24, 0x100
	s_addc_u32 s25, s25, 0
	s_add_u32 s50, s50, 0x100
	s_addc_u32 s51, s51, 0
	s_cmp_gt_u32 s56, 13
	s_cbranch_scc0 .LBB0_1058
	s_and_b64 vcc, exec, s[20:21]
	s_cbranch_vccz .LBB0_1061
	s_barrier

.Lq5_w1:
	s_waitcnt lgkmcnt(0)
	s_barrier
	s_waitcnt lgkmcnt(0)
	v_mfma_f32_16x16x32_bf16 v[128:131], v[148:151], v[188:191], v[128:131]
	v_mfma_f32_16x16x32_bf16 v[124:127], v[156:159], v[188:191], v[124:127]
	v_mfma_f32_16x16x32_bf16 v[120:123], v[148:151], v[180:183], v[120:123]
	v_mfma_f32_16x16x32_bf16 v[116:119], v[156:159], v[180:183], v[116:119]
	v_mfma_f32_16x16x32_bf16 v[104:107], v[148:151], v[172:175], v[104:107]
	v_mfma_f32_16x16x32_bf16 v[100:103], v[156:159], v[172:175], v[100:103]
	v_mfma_f32_16x16x32_bf16 v[88:91], v[148:151], v[164:167], v[88:91]
	v_mfma_f32_16x16x32_bf16 v[84:87], v[156:159], v[164:167], v[84:87]
	v_mfma_f32_16x16x32_bf16 v[128:131], v[152:155], v[192:195], v[128:131]
	v_mfma_f32_16x16x32_bf16 v[124:127], v[160:163], v[192:195], v[124:127]
	v_mfma_f32_16x16x32_bf16 v[120:123], v[152:155], v[184:187], v[120:123]
	v_mfma_f32_16x16x32_bf16 v[116:119], v[160:163], v[184:187], v[116:119]
	v_mfma_f32_16x16x32_bf16 v[104:107], v[152:155], v[176:179], v[104:107]
	v_mfma_f32_16x16x32_bf16 v[100:103], v[160:163], v[176:179], v[100:103]
	v_mfma_f32_16x16x32_bf16 v[88:91], v[152:155], v[168:171], v[88:91]
	v_mfma_f32_16x16x32_bf16 v[84:87], v[160:163], v[168:171], v[84:87]
	v_cmp_ne_u32_e64 s[2:3], 1, v217
	s_andn2_b64 vcc, exec, s[26:27]
	s_cbranch_vccnz .LBB0_1134
	v_mfma_f32_16x16x32_bf16 v[112:115], v[132:135], v[188:191], v[112:115]
	v_mfma_f32_16x16x32_bf16 v[108:111], v[140:143], v[188:191], v[108:111]
	v_mfma_f32_16x16x32_bf16 v[96:99], v[132:135], v[180:183], v[96:99]
	v_mfma_f32_16x16x32_bf16 v[92:95], v[140:143], v[180:183], v[92:95]
	v_mfma_f32_16x16x32_bf16 v[80:83], v[132:135], v[172:175], v[80:83]
	v_mfma_f32_16x16x32_bf16 v[76:79], v[140:143], v[172:175], v[76:79]
	v_mfma_f32_16x16x32_bf16 v[72:75], v[132:135], v[164:167], v[72:75]
	v_mfma_f32_16x16x32_bf16 v[68:71], v[140:143], v[164:167], v[68:71]
	v_mfma_f32_16x16x32_bf16 v[112:115], v[136:139], v[192:195], v[112:115]
	v_mfma_f32_16x16x32_bf16 v[108:111], v[144:147], v[192:195], v[108:111]
	v_mfma_f32_16x16x32_bf16 v[96:99], v[136:139], v[184:187], v[96:99]
	v_mfma_f32_16x16x32_bf16 v[92:95], v[144:147], v[184:187], v[92:95]
	v_mfma_f32_16x16x32_bf16 v[80:83], v[136:139], v[176:179], v[80:83]
	v_mfma_f32_16x16x32_bf16 v[76:79], v[144:147], v[176:179], v[76:79]
	v_mfma_f32_16x16x32_bf16 v[72:75], v[136:139], v[168:171], v[72:75]
	v_mfma_f32_16x16x32_bf16 v[68:71], v[144:147], v[168:171], v[68:71]

.Lq5_w2:
	s_waitcnt lgkmcnt(0)
	s_barrier
	s_cbranch_vccnz .LBB0_1136
	s_waitcnt lgkmcnt(0)
	v_mfma_f32_16x16x32_bf16 v[64:67], v[148:151], v[188:191], v[64:67]
	v_mfma_f32_16x16x32_bf16 v[60:63], v[156:159], v[188:191], v[60:63]
	v_mfma_f32_16x16x32_bf16 v[48:51], v[148:151], v[180:183], v[48:51]
	v_mfma_f32_16x16x32_bf16 v[44:47], v[156:159], v[180:183], v[44:47]
	v_mfma_f32_16x16x32_bf16 v[32:35], v[148:151], v[172:175], v[32:35]
	v_mfma_f32_16x16x32_bf16 v[28:31], v[156:159], v[172:175], v[28:31]
	v_mfma_f32_16x16x32_bf16 v[16:19], v[148:151], v[164:167], v[16:19]
	v_mfma_f32_16x16x32_bf16 v[12:15], v[156:159], v[164:167], v[12:15]
	v_mfma_f32_16x16x32_bf16 v[64:67], v[152:155], v[192:195], v[64:67]
	v_mfma_f32_16x16x32_bf16 v[60:63], v[160:163], v[192:195], v[60:63]
	v_mfma_f32_16x16x32_bf16 v[48:51], v[152:155], v[184:187], v[48:51]
	v_mfma_f32_16x16x32_bf16 v[44:47], v[160:163], v[184:187], v[44:47]
	v_mfma_f32_16x16x32_bf16 v[32:35], v[152:155], v[176:179], v[32:35]
	v_mfma_f32_16x16x32_bf16 v[28:31], v[160:163], v[176:179], v[28:31]
	v_mfma_f32_16x16x32_bf16 v[16:19], v[152:155], v[168:171], v[16:19]
	v_mfma_f32_16x16x32_bf16 v[12:15], v[160:163], v[168:171], v[12:15]
	v_mfma_f32_16x16x32_bf16 v[56:59], v[132:135], v[188:191], v[56:59]
	v_mfma_f32_16x16x32_bf16 v[52:55], v[140:143], v[188:191], v[52:55]
	v_mfma_f32_16x16x32_bf16 v[40:43], v[132:135], v[180:183], v[40:43]
	v_mfma_f32_16x16x32_bf16 v[36:39], v[140:143], v[180:183], v[36:39]
	v_mfma_f32_16x16x32_bf16 v[24:27], v[132:135], v[172:175], v[24:27]
	v_mfma_f32_16x16x32_bf16 v[20:23], v[140:143], v[172:175], v[20:23]
	v_mfma_f32_16x16x32_bf16 v[8:11], v[132:135], v[164:167], v[8:11]
	v_mfma_f32_16x16x32_bf16 v[4:7], v[140:143], v[164:167], v[4:7]
	v_mfma_f32_16x16x32_bf16 v[56:59], v[136:139], v[192:195], v[56:59]
	v_mfma_f32_16x16x32_bf16 v[52:55], v[144:147], v[192:195], v[52:55]
	v_mfma_f32_16x16x32_bf16 v[40:43], v[136:139], v[184:187], v[40:43]
	v_mfma_f32_16x16x32_bf16 v[36:39], v[144:147], v[184:187], v[36:39]
	v_mfma_f32_16x16x32_bf16 v[24:27], v[136:139], v[176:179], v[24:27]
	v_mfma_f32_16x16x32_bf16 v[20:23], v[144:147], v[176:179], v[20:23]
	v_mfma_f32_16x16x32_bf16 v[8:11], v[136:139], v[168:171], v[8:11]
	v_mfma_f32_16x16x32_bf16 v[4:7], v[144:147], v[168:171], v[4:7]

.Lq5_w3:
	s_waitcnt lgkmcnt(0)
	s_barrier
	s_waitcnt lgkmcnt(0)
	v_mfma_f32_16x16x32_bf16 v[128:131], v[148:151], v[188:191], v[128:131]
	v_mfma_f32_16x16x32_bf16 v[124:127], v[156:159], v[188:191], v[124:127]
	v_mfma_f32_16x16x32_bf16 v[120:123], v[148:151], v[180:183], v[120:123]
	v_mfma_f32_16x16x32_bf16 v[116:119], v[156:159], v[180:183], v[116:119]
	v_mfma_f32_16x16x32_bf16 v[104:107], v[148:151], v[172:175], v[104:107]
	v_mfma_f32_16x16x32_bf16 v[100:103], v[156:159], v[172:175], v[100:103]
	v_mfma_f32_16x16x32_bf16 v[88:91], v[148:151], v[164:167], v[88:91]
	v_mfma_f32_16x16x32_bf16 v[84:87], v[156:159], v[164:167], v[84:87]
	v_mfma_f32_16x16x32_bf16 v[128:131], v[152:155], v[192:195], v[128:131]
	v_mfma_f32_16x16x32_bf16 v[124:127], v[160:163], v[192:195], v[124:127]
	v_mfma_f32_16x16x32_bf16 v[120:123], v[152:155], v[184:187], v[120:123]
	v_mfma_f32_16x16x32_bf16 v[116:119], v[160:163], v[184:187], v[116:119]
	v_mfma_f32_16x16x32_bf16 v[104:107], v[152:155], v[176:179], v[104:107]
	v_mfma_f32_16x16x32_bf16 v[100:103], v[160:163], v[176:179], v[100:103]
	v_mfma_f32_16x16x32_bf16 v[88:91], v[152:155], v[168:171], v[88:91]
	v_mfma_f32_16x16x32_bf16 v[84:87], v[160:163], v[168:171], v[84:87]
	s_and_b64 vcc, exec, s[2:3]
	s_cbranch_vccnz .LBB0_1138
	v_mfma_f32_16x16x32_bf16 v[112:115], v[132:135], v[188:191], v[112:115]
	v_mfma_f32_16x16x32_bf16 v[108:111], v[140:143], v[188:191], v[108:111]
	v_mfma_f32_16x16x32_bf16 v[96:99], v[132:135], v[180:183], v[96:99]
	v_mfma_f32_16x16x32_bf16 v[92:95], v[140:143], v[180:183], v[92:95]
	v_mfma_f32_16x16x32_bf16 v[80:83], v[132:135], v[172:175], v[80:83]
	v_mfma_f32_16x16x32_bf16 v[76:79], v[140:143], v[172:175], v[76:79]
	v_mfma_f32_16x16x32_bf16 v[72:75], v[132:135], v[164:167], v[72:75]
	v_mfma_f32_16x16x32_bf16 v[68:71], v[140:143], v[164:167], v[68:71]
	v_mfma_f32_16x16x32_bf16 v[112:115], v[136:139], v[192:195], v[112:115]
	v_mfma_f32_16x16x32_bf16 v[108:111], v[144:147], v[192:195], v[108:111]
	v_mfma_f32_16x16x32_bf16 v[96:99], v[136:139], v[184:187], v[96:99]
	v_mfma_f32_16x16x32_bf16 v[92:95], v[144:147], v[184:187], v[92:95]
	v_mfma_f32_16x16x32_bf16 v[80:83], v[136:139], v[176:179], v[80:83]
	v_mfma_f32_16x16x32_bf16 v[76:79], v[144:147], v[176:179], v[76:79]
	v_mfma_f32_16x16x32_bf16 v[72:75], v[136:139], v[168:171], v[72:75]
	v_mfma_f32_16x16x32_bf16 v[68:71], v[144:147], v[168:171], v[68:71]

.Lq5_w4:
	s_waitcnt lgkmcnt(0)
	s_barrier
	s_cbranch_vccnz .LBB0_1131
	s_waitcnt lgkmcnt(0)
	v_mfma_f32_16x16x32_bf16 v[64:67], v[148:151], v[188:191], v[64:67]
	v_mfma_f32_16x16x32_bf16 v[60:63], v[156:159], v[188:191], v[60:63]
	v_mfma_f32_16x16x32_bf16 v[48:51], v[148:151], v[180:183], v[48:51]
	v_mfma_f32_16x16x32_bf16 v[44:47], v[156:159], v[180:183], v[44:47]
	v_mfma_f32_16x16x32_bf16 v[32:35], v[148:151], v[172:175], v[32:35]
	v_mfma_f32_16x16x32_bf16 v[28:31], v[156:159], v[172:175], v[28:31]
	v_mfma_f32_16x16x32_bf16 v[16:19], v[148:151], v[164:167], v[16:19]
	v_mfma_f32_16x16x32_bf16 v[12:15], v[156:159], v[164:167], v[12:15]
	v_mfma_f32_16x16x32_bf16 v[64:67], v[152:155], v[192:195], v[64:67]
	v_mfma_f32_16x16x32_bf16 v[60:63], v[160:163], v[192:195], v[60:63]
	v_mfma_f32_16x16x32_bf16 v[48:51], v[152:155], v[184:187], v[48:51]
	v_mfma_f32_16x16x32_bf16 v[44:47], v[160:163], v[184:187], v[44:47]
	v_mfma_f32_16x16x32_bf16 v[32:35], v[152:155], v[176:179], v[32:35]
	v_mfma_f32_16x16x32_bf16 v[28:31], v[160:163], v[176:179], v[28:31]
	v_mfma_f32_16x16x32_bf16 v[16:19], v[152:155], v[168:171], v[16:19]
	v_mfma_f32_16x16x32_bf16 v[12:15], v[160:163], v[168:171], v[12:15]
	v_mfma_f32_16x16x32_bf16 v[56:59], v[132:135], v[188:191], v[56:59]
	v_mfma_f32_16x16x32_bf16 v[52:55], v[140:143], v[188:191], v[52:55]
	v_mfma_f32_16x16x32_bf16 v[40:43], v[132:135], v[180:183], v[40:43]
	v_mfma_f32_16x16x32_bf16 v[36:39], v[140:143], v[180:183], v[36:39]
	v_mfma_f32_16x16x32_bf16 v[24:27], v[132:135], v[172:175], v[24:27]
	v_mfma_f32_16x16x32_bf16 v[20:23], v[140:143], v[172:175], v[20:23]
	v_mfma_f32_16x16x32_bf16 v[8:11], v[132:135], v[164:167], v[8:11]
	v_mfma_f32_16x16x32_bf16 v[2:5], v[140:143], v[164:167], v[4:7]
	v_mfma_f32_16x16x32_bf16 v[56:59], v[136:139], v[192:195], v[56:59]
	v_mfma_f32_16x16x32_bf16 v[52:55], v[144:147], v[192:195], v[52:55]
	v_mfma_f32_16x16x32_bf16 v[40:43], v[136:139], v[184:187], v[40:43]
	v_mfma_f32_16x16x32_bf16 v[36:39], v[144:147], v[184:187], v[36:39]
	v_mfma_f32_16x16x32_bf16 v[24:27], v[136:139], v[176:179], v[24:27]
	v_mfma_f32_16x16x32_bf16 v[20:23], v[144:147], v[176:179], v[20:23]
	v_mfma_f32_16x16x32_bf16 v[8:11], v[136:139], v[168:171], v[8:11]
	v_mfma_f32_16x16x32_bf16 v[4:7], v[144:147], v[168:171], v[2:5]
	s_branch .LBB0_1131

.Lq6_w1:
	s_waitcnt lgkmcnt(0)
	s_barrier
	s_waitcnt lgkmcnt(0)
	v_mfma_f32_16x16x32_bf16 v[68:71], v[180:183], v[220:223], v[160:163]
	v_mfma_f32_16x16x32_bf16 v[72:75], v[188:191], v[220:223], v[156:159]
	v_mfma_f32_16x16x32_bf16 v[76:79], v[180:183], v[212:215], v[152:155]
	v_mfma_f32_16x16x32_bf16 v[80:83], v[188:191], v[212:215], v[148:151]
	v_mfma_f32_16x16x32_bf16 v[84:87], v[180:183], v[204:207], v[136:139]
	v_mfma_f32_16x16x32_bf16 v[92:95], v[188:191], v[204:207], v[132:135]
	v_mfma_f32_16x16x32_bf16 v[96:99], v[180:183], v[196:199], v[120:123]
	v_mfma_f32_16x16x32_bf16 v[100:103], v[188:191], v[196:199], v[112:115]
	v_mfma_f32_16x16x32_bf16 v[68:71], v[184:187], v[224:227], v[68:71]
	v_mfma_f32_16x16x32_bf16 v[72:75], v[192:195], v[224:227], v[72:75]
	v_mfma_f32_16x16x32_bf16 v[76:79], v[184:187], v[216:219], v[76:79]
	v_mfma_f32_16x16x32_bf16 v[80:83], v[192:195], v[216:219], v[80:83]
	v_mfma_f32_16x16x32_bf16 v[84:87], v[184:187], v[208:211], v[84:87]
	v_mfma_f32_16x16x32_bf16 v[92:95], v[192:195], v[208:211], v[92:95]
	v_mfma_f32_16x16x32_bf16 v[96:99], v[184:187], v[200:203], v[96:99]
	v_mfma_f32_16x16x32_bf16 v[100:103], v[192:195], v[200:203], v[100:103]
	v_cmp_ne_u32_e64 s[4:5], 1, v251
	s_andn2_b64 vcc, exec, s[34:35]
	s_cbranch_vccnz .LBB0_1285
	v_mfma_f32_16x16x32_bf16 v[112:115], v[164:167], v[220:223], v[144:147]
	v_mfma_f32_16x16x32_bf16 v[144:147], v[168:171], v[224:227], v[112:115]
	v_mfma_f32_16x16x32_bf16 v[112:115], v[172:175], v[220:223], v[140:143]
	v_mfma_f32_16x16x32_bf16 v[140:143], v[176:179], v[224:227], v[112:115]
	v_mfma_f32_16x16x32_bf16 v[112:115], v[164:167], v[212:215], v[128:131]
	v_mfma_f32_16x16x32_bf16 v[128:131], v[168:171], v[216:219], v[112:115]
	v_mfma_f32_16x16x32_bf16 v[112:115], v[172:175], v[212:215], v[124:127]
	v_mfma_f32_16x16x32_bf16 v[124:127], v[176:179], v[216:219], v[112:115]
	v_mfma_f32_16x16x32_bf16 v[112:115], v[164:167], v[204:207], v[116:119]
	v_mfma_f32_16x16x32_bf16 v[108:111], v[172:175], v[204:207], v[108:111]
	v_mfma_f32_16x16x32_bf16 v[104:107], v[164:167], v[196:199], v[104:107]
	v_mfma_f32_16x16x32_bf16 v[88:91], v[172:175], v[196:199], v[88:91]
	v_mfma_f32_16x16x32_bf16 v[116:119], v[168:171], v[208:211], v[112:115]
	v_mfma_f32_16x16x32_bf16 v[108:111], v[176:179], v[208:211], v[108:111]
	v_mfma_f32_16x16x32_bf16 v[104:107], v[168:171], v[200:203], v[104:107]
	v_mfma_f32_16x16x32_bf16 v[88:91], v[176:179], v[200:203], v[88:91]

.Lq6_w2:
	s_waitcnt lgkmcnt(0)
	s_barrier
	s_cbranch_vccnz .LBB0_1287
	s_waitcnt lgkmcnt(0)
	v_mfma_f32_16x16x32_bf16 v[64:67], v[180:183], v[156:159], v[64:67]
	v_mfma_f32_16x16x32_bf16 v[60:63], v[188:191], v[156:159], v[60:63]
	v_mfma_f32_16x16x32_bf16 v[48:51], v[180:183], v[148:151], v[48:51]
	v_mfma_f32_16x16x32_bf16 v[44:47], v[188:191], v[148:151], v[44:47]
	v_mfma_f32_16x16x32_bf16 v[32:35], v[180:183], v[132:135], v[32:35]
	v_mfma_f32_16x16x32_bf16 v[28:31], v[188:191], v[132:135], v[28:31]
	v_mfma_f32_16x16x32_bf16 v[16:19], v[180:183], v[112:115], v[16:19]
	v_mfma_f32_16x16x32_bf16 v[12:15], v[188:191], v[112:115], v[12:15]
	v_mfma_f32_16x16x32_bf16 v[64:67], v[184:187], v[160:163], v[64:67]
	v_mfma_f32_16x16x32_bf16 v[60:63], v[192:195], v[160:163], v[60:63]
	v_mfma_f32_16x16x32_bf16 v[48:51], v[184:187], v[152:155], v[48:51]
	v_mfma_f32_16x16x32_bf16 v[44:47], v[192:195], v[152:155], v[44:47]
	v_mfma_f32_16x16x32_bf16 v[32:35], v[184:187], v[136:139], v[32:35]
	v_mfma_f32_16x16x32_bf16 v[28:31], v[192:195], v[136:139], v[28:31]
	v_mfma_f32_16x16x32_bf16 v[16:19], v[184:187], v[120:123], v[16:19]
	v_mfma_f32_16x16x32_bf16 v[12:15], v[192:195], v[120:123], v[12:15]
	v_mfma_f32_16x16x32_bf16 v[56:59], v[164:167], v[156:159], v[56:59]
	v_mfma_f32_16x16x32_bf16 v[52:55], v[172:175], v[156:159], v[52:55]
	v_mfma_f32_16x16x32_bf16 v[40:43], v[164:167], v[148:151], v[40:43]
	v_mfma_f32_16x16x32_bf16 v[36:39], v[172:175], v[148:151], v[36:39]
	v_mfma_f32_16x16x32_bf16 v[24:27], v[164:167], v[132:135], v[24:27]
	v_mfma_f32_16x16x32_bf16 v[20:23], v[172:175], v[132:135], v[20:23]
	v_mfma_f32_16x16x32_bf16 v[8:11], v[164:167], v[112:115], v[8:11]
	v_mfma_f32_16x16x32_bf16 v[4:7], v[172:175], v[112:115], v[4:7]
	v_mfma_f32_16x16x32_bf16 v[56:59], v[168:171], v[160:163], v[56:59]
	v_mfma_f32_16x16x32_bf16 v[52:55], v[176:179], v[160:163], v[52:55]
	v_mfma_f32_16x16x32_bf16 v[40:43], v[168:171], v[152:155], v[40:43]
	v_mfma_f32_16x16x32_bf16 v[36:39], v[176:179], v[152:155], v[36:39]
	v_mfma_f32_16x16x32_bf16 v[24:27], v[168:171], v[136:139], v[24:27]
	v_mfma_f32_16x16x32_bf16 v[20:23], v[176:179], v[136:139], v[20:23]
	v_mfma_f32_16x16x32_bf16 v[8:11], v[168:171], v[120:123], v[8:11]
	v_mfma_f32_16x16x32_bf16 v[4:7], v[176:179], v[120:123], v[4:7]

.Lq6_w3:
	s_waitcnt lgkmcnt(0)
	s_barrier
	s_waitcnt lgkmcnt(0)
	v_mfma_f32_16x16x32_bf16 v[68:71], v[180:183], v[220:223], v[68:71]
	v_mfma_f32_16x16x32_bf16 v[160:163], v[184:187], v[224:227], v[68:71]
	v_mfma_f32_16x16x32_bf16 v[68:71], v[188:191], v[220:223], v[72:75]
	v_mfma_f32_16x16x32_bf16 v[156:159], v[192:195], v[224:227], v[68:71]
	v_mfma_f32_16x16x32_bf16 v[68:71], v[180:183], v[212:215], v[76:79]
	v_mfma_f32_16x16x32_bf16 v[152:155], v[184:187], v[216:219], v[68:71]
	v_mfma_f32_16x16x32_bf16 v[68:71], v[188:191], v[212:215], v[80:83]
	v_mfma_f32_16x16x32_bf16 v[148:151], v[192:195], v[216:219], v[68:71]
	v_mfma_f32_16x16x32_bf16 v[68:71], v[180:183], v[204:207], v[84:87]
	v_mfma_f32_16x16x32_bf16 v[136:139], v[184:187], v[208:211], v[68:71]
	v_mfma_f32_16x16x32_bf16 v[68:71], v[188:191], v[204:207], v[92:95]
	v_mfma_f32_16x16x32_bf16 v[132:135], v[192:195], v[208:211], v[68:71]
	v_mfma_f32_16x16x32_bf16 v[68:71], v[180:183], v[196:199], v[96:99]
	v_mfma_f32_16x16x32_bf16 v[120:123], v[184:187], v[200:203], v[68:71]
	v_mfma_f32_16x16x32_bf16 v[68:71], v[188:191], v[196:199], v[100:103]
	v_mfma_f32_16x16x32_bf16 v[112:115], v[192:195], v[200:203], v[68:71]
	s_and_b64 vcc, exec, s[4:5]
	s_cbranch_vccnz .LBB0_1289
	v_mfma_f32_16x16x32_bf16 v[68:71], v[164:167], v[220:223], v[144:147]
	v_mfma_f32_16x16x32_bf16 v[144:147], v[168:171], v[224:227], v[68:71]
	v_mfma_f32_16x16x32_bf16 v[68:71], v[172:175], v[220:223], v[140:143]
	v_mfma_f32_16x16x32_bf16 v[140:143], v[176:179], v[224:227], v[68:71]
	v_mfma_f32_16x16x32_bf16 v[68:71], v[164:167], v[212:215], v[128:131]
	v_mfma_f32_16x16x32_bf16 v[128:131], v[168:171], v[216:219], v[68:71]
	v_mfma_f32_16x16x32_bf16 v[68:71], v[172:175], v[212:215], v[124:127]
	v_mfma_f32_16x16x32_bf16 v[124:127], v[176:179], v[216:219], v[68:71]
	v_mfma_f32_16x16x32_bf16 v[68:71], v[164:167], v[204:207], v[116:119]
	v_mfma_f32_16x16x32_bf16 v[116:119], v[168:171], v[208:211], v[68:71]
	v_mfma_f32_16x16x32_bf16 v[68:71], v[172:175], v[204:207], v[108:111]
	v_mfma_f32_16x16x32_bf16 v[108:111], v[176:179], v[208:211], v[68:71]
	v_mfma_f32_16x16x32_bf16 v[68:71], v[164:167], v[196:199], v[104:107]
	v_mfma_f32_16x16x32_bf16 v[104:107], v[168:171], v[200:203], v[68:71]
	v_mfma_f32_16x16x32_bf16 v[68:71], v[172:175], v[196:199], v[88:91]
	v_mfma_f32_16x16x32_bf16 v[88:91], v[176:179], v[200:203], v[68:71]

.Lq6_w4:
	s_waitcnt lgkmcnt(0)
	s_barrier
	s_cbranch_vccnz .LBB0_1282
	s_waitcnt lgkmcnt(0)
	v_mfma_f32_16x16x32_bf16 v[64:67], v[180:183], v[96:99], v[64:67]
	v_mfma_f32_16x16x32_bf16 v[60:63], v[188:191], v[96:99], v[60:63]
	v_mfma_f32_16x16x32_bf16 v[48:51], v[180:183], v[84:87], v[48:51]
	v_mfma_f32_16x16x32_bf16 v[44:47], v[188:191], v[84:87], v[44:47]
	v_mfma_f32_16x16x32_bf16 v[32:35], v[180:183], v[76:79], v[32:35]
	v_mfma_f32_16x16x32_bf16 v[28:31], v[188:191], v[76:79], v[28:31]
	v_mfma_f32_16x16x32_bf16 v[16:19], v[180:183], v[68:71], v[16:19]
	v_mfma_f32_16x16x32_bf16 v[12:15], v[188:191], v[68:71], v[12:15]
	v_mfma_f32_16x16x32_bf16 v[64:67], v[184:187], v[100:103], v[64:67]
	v_mfma_f32_16x16x32_bf16 v[60:63], v[192:195], v[100:103], v[60:63]
	v_mfma_f32_16x16x32_bf16 v[48:51], v[184:187], v[92:95], v[48:51]
	v_mfma_f32_16x16x32_bf16 v[44:47], v[192:195], v[92:95], v[44:47]
	v_mfma_f32_16x16x32_bf16 v[32:35], v[184:187], v[80:83], v[32:35]
	v_mfma_f32_16x16x32_bf16 v[28:31], v[192:195], v[80:83], v[28:31]
	v_mfma_f32_16x16x32_bf16 v[16:19], v[184:187], v[72:75], v[16:19]
	v_mfma_f32_16x16x32_bf16 v[12:15], v[192:195], v[72:75], v[12:15]
	v_mfma_f32_16x16x32_bf16 v[56:59], v[164:167], v[96:99], v[56:59]
	v_mfma_f32_16x16x32_bf16 v[52:55], v[172:175], v[96:99], v[52:55]
	v_mfma_f32_16x16x32_bf16 v[40:43], v[164:167], v[84:87], v[40:43]
	v_mfma_f32_16x16x32_bf16 v[36:39], v[172:175], v[84:87], v[36:39]
	v_mfma_f32_16x16x32_bf16 v[24:27], v[164:167], v[76:79], v[24:27]
	v_mfma_f32_16x16x32_bf16 v[20:23], v[172:175], v[76:79], v[20:23]
	v_mfma_f32_16x16x32_bf16 v[8:11], v[164:167], v[68:71], v[8:11]
	v_mfma_f32_16x16x32_bf16 v[2:5], v[172:175], v[68:71], v[4:7]
	v_mfma_f32_16x16x32_bf16 v[56:59], v[168:171], v[100:103], v[56:59]
	v_mfma_f32_16x16x32_bf16 v[52:55], v[176:179], v[100:103], v[52:55]
	v_mfma_f32_16x16x32_bf16 v[40:43], v[168:171], v[92:95], v[40:43]
	v_mfma_f32_16x16x32_bf16 v[36:39], v[176:179], v[92:95], v[36:39]
	v_mfma_f32_16x16x32_bf16 v[24:27], v[168:171], v[80:83], v[24:27]
	v_mfma_f32_16x16x32_bf16 v[20:23], v[176:179], v[80:83], v[20:23]
	v_mfma_f32_16x16x32_bf16 v[8:11], v[168:171], v[72:75], v[8:11]
	v_mfma_f32_16x16x32_bf16 v[4:7], v[176:179], v[72:75], v[2:5]
	s_branch .LBB0_1282

.LBB0_1391:
	ds_read_b128 v[24:27], v234
	ds_read_b128 v[28:31], v234 offset:1024
	ds_read_b128 v[96:99], v234 offset:2048
	ds_read_b128 v[100:103], v234 offset:3072
	ds_read_b128 v[144:147], v235
	ds_read_b128 v[148:151], v235 offset:1024
	ds_read_b128 v[152:155], v235 offset:2048
	ds_read_b128 v[156:159], v235 offset:3072
	s_add_u32 s16, s14, 0xfff80080
	s_addc_u32 s17, s15, -1
	s_cmp_eq_u32 s22, 28
	s_cselect_b32 s19, s9, s17
	s_cselect_b32 s18, s13, s16
	s_cselect_b32 s17, s79, s21
	s_cselect_b32 s16, s78, s20
	v_lshl_add_u64 v[204:205], s[14:15], 0, v[192:193]
	s_add_i32 m0, s49, 0xc000
	ds_read_b128 v[160:163], v236
	ds_read_b128 v[164:167], v236 offset:1024
	ds_read_b128 v[168:171], v236 offset:2048
	ds_read_b128 v[172:175], v236 offset:3072
	ds_read_b128 v[176:179], v236 offset:4096
	ds_read_b128 v[180:183], v236 offset:5120
	ds_read_b128 v[196:199], v236 offset:6144
	ds_read_b128 v[200:203], v236 offset:7168
	global_load_lds_dwordx4 v[204:205], off
	v_lshl_add_u64 v[204:205], s[14:15], 0, v[194:195]
	s_add_i32 m0, s49, 0xe000
	s_nop 0
	global_load_lds_dwordx4 v[204:205], off
	s_waitcnt vmcnt(8)
	s_waitcnt lgkmcnt(0)
	s_barrier
	s_waitcnt lgkmcnt(0)
	v_mfma_f32_16x16x32_bf16 v[140:143], v[24:27], v[160:163], v[140:143]
	v_mfma_f32_16x16x32_bf16 v[84:87], v[96:99], v[160:163], v[84:87]
	v_mfma_f32_16x16x32_bf16 v[116:119], v[24:27], v[168:171], v[116:119]
	v_mfma_f32_16x16x32_bf16 v[44:47], v[96:99], v[168:171], v[44:47]
	v_mfma_f32_16x16x32_bf16 v[108:111], v[24:27], v[176:179], v[108:111]
	v_mfma_f32_16x16x32_bf16 v[36:39], v[96:99], v[176:179], v[36:39]
	v_mfma_f32_16x16x32_bf16 v[136:139], v[24:27], v[196:199], v[136:139]
	v_mfma_f32_16x16x32_bf16 v[56:59], v[96:99], v[196:199], v[56:59]
	v_mfma_f32_16x16x32_bf16 v[140:143], v[28:31], v[164:167], v[140:143]
	v_mfma_f32_16x16x32_bf16 v[84:87], v[100:103], v[164:167], v[84:87]
	v_mfma_f32_16x16x32_bf16 v[116:119], v[28:31], v[172:175], v[116:119]
	v_mfma_f32_16x16x32_bf16 v[44:47], v[100:103], v[172:175], v[44:47]
	v_mfma_f32_16x16x32_bf16 v[108:111], v[28:31], v[180:183], v[108:111]
	v_mfma_f32_16x16x32_bf16 v[36:39], v[100:103], v[180:183], v[36:39]
	v_mfma_f32_16x16x32_bf16 v[136:139], v[28:31], v[200:203], v[136:139]
	v_mfma_f32_16x16x32_bf16 v[56:59], v[100:103], v[200:203], v[56:59]
	v_mfma_f32_16x16x32_bf16 v[128:131], v[144:147], v[160:163], v[128:131]
	v_mfma_f32_16x16x32_bf16 v[80:83], v[152:155], v[160:163], v[80:83]
	v_mfma_f32_16x16x32_bf16 v[112:115], v[144:147], v[168:171], v[112:115]
	v_mfma_f32_16x16x32_bf16 v[40:43], v[152:155], v[168:171], v[40:43]
	v_mfma_f32_16x16x32_bf16 v[104:107], v[144:147], v[176:179], v[104:107]
	v_mfma_f32_16x16x32_bf16 v[32:35], v[152:155], v[176:179], v[32:35]
	v_mfma_f32_16x16x32_bf16 v[132:135], v[144:147], v[196:199], v[132:135]
	v_mfma_f32_16x16x32_bf16 v[60:63], v[152:155], v[196:199], v[60:63]
	v_mfma_f32_16x16x32_bf16 v[128:131], v[148:151], v[164:167], v[128:131]
	v_mfma_f32_16x16x32_bf16 v[80:83], v[156:159], v[164:167], v[80:83]
	v_mfma_f32_16x16x32_bf16 v[112:115], v[148:151], v[172:175], v[112:115]
	v_mfma_f32_16x16x32_bf16 v[40:43], v[156:159], v[172:175], v[40:43]
	v_mfma_f32_16x16x32_bf16 v[104:107], v[148:151], v[180:183], v[104:107]
	v_mfma_f32_16x16x32_bf16 v[32:35], v[156:159], v[180:183], v[32:35]
	v_mfma_f32_16x16x32_bf16 v[132:135], v[148:151], v[200:203], v[132:135]
	v_mfma_f32_16x16x32_bf16 v[60:63], v[156:159], v[200:203], v[60:63]
	s_barrier
	s_add_i32 s23, s45, s51
	v_lshl_add_u64 v[204:205], s[16:17], 0, v[188:189]
	s_mov_b32 m0, s23
	ds_read_b128 v[160:163], v236 offset:16384
	ds_read_b128 v[164:167], v236 offset:17408
	ds_read_b128 v[168:171], v236 offset:18432
	ds_read_b128 v[172:175], v236 offset:19456
	ds_read_b128 v[176:179], v236 offset:20480
	ds_read_b128 v[180:183], v236 offset:21504
	ds_read_b128 v[196:199], v236 offset:22528
	ds_read_b128 v[200:203], v236 offset:23552
	global_load_lds_dwordx4 v[204:205], off
	s_add_i32 m0, s23, 0x2000
	s_add_u32 s24, s16, 0x84000
	v_lshl_add_u64 v[206:207], s[16:17], 0, v[184:185]
	s_addc_u32 s25, s17, 0
	s_add_i32 s23, s48, s51
	global_load_lds_dwordx4 v[206:207], off
	v_lshl_add_u64 v[208:209], s[24:25], 0, v[188:189]
	s_mov_b32 m0, s23
	v_lshl_add_u64 v[210:211], s[18:19], 0, v[186:187]
	global_load_lds_dwordx4 v[208:209], off
	v_lshl_add_u64 v[208:209], s[24:25], 0, v[184:185]
	s_add_i32 m0, s23, 0x2000
	s_nop 0
	global_load_lds_dwordx4 v[208:209], off
	v_lshl_add_u64 v[208:209], s[18:19], 0, v[190:191]
	s_mov_b32 m0, s49
	s_nop 0
	global_load_lds_dwordx4 v[208:209], off
	s_mov_b32 m0, s50
	s_nop 0
	global_load_lds_dwordx4 v[210:211], off
	s_waitcnt vmcnt(8)
	s_waitcnt lgkmcnt(0)
	s_barrier
	s_waitcnt lgkmcnt(0)
	v_mfma_f32_16x16x32_bf16 v[124:127], v[24:27], v[160:163], v[124:127]
	v_mfma_f32_16x16x32_bf16 v[52:55], v[96:99], v[160:163], v[52:55]
	v_mfma_f32_16x16x32_bf16 v[76:79], v[24:27], v[168:171], v[76:79]
	v_mfma_f32_16x16x32_bf16 v[12:15], v[96:99], v[168:171], v[12:15]
	v_mfma_f32_16x16x32_bf16 v[68:71], v[24:27], v[176:179], v[68:71]
	v_mfma_f32_16x16x32_bf16 v[4:7], v[96:99], v[176:179], v[4:7]
	v_mfma_f32_16x16x32_bf16 v[16:19], v[96:99], v[196:199], v[16:19]
	v_mfma_f32_16x16x32_bf16 v[124:127], v[28:31], v[164:167], v[124:127]
	v_mfma_f32_16x16x32_bf16 v[52:55], v[100:103], v[164:167], v[52:55]
	v_mfma_f32_16x16x32_bf16 v[76:79], v[28:31], v[172:175], v[76:79]
	v_mfma_f32_16x16x32_bf16 v[12:15], v[100:103], v[172:175], v[12:15]
	v_mfma_f32_16x16x32_bf16 v[68:71], v[28:31], v[180:183], v[68:71]
	v_mfma_f32_16x16x32_bf16 v[4:7], v[100:103], v[180:183], v[4:7]
	v_mfma_f32_16x16x32_bf16 v[24:27], v[24:27], v[196:199], v[88:91]
	v_mfma_f32_16x16x32_bf16 v[16:19], v[100:103], v[200:203], v[16:19]
	v_mfma_f32_16x16x32_bf16 v[24:27], v[28:31], v[200:203], v[24:27]
	v_mfma_f32_16x16x32_bf16 v[48:51], v[152:155], v[160:163], v[48:51]
	v_mfma_f32_16x16x32_bf16 v[72:75], v[144:147], v[168:171], v[72:75]
	v_mfma_f32_16x16x32_bf16 v[8:11], v[152:155], v[168:171], v[8:11]
	v_mfma_f32_16x16x32_bf16 v[64:67], v[144:147], v[176:179], v[64:67]
	v_mfma_f32_16x16x32_bf16 v[0:3], v[152:155], v[176:179], v[0:3]
	v_mfma_f32_16x16x32_bf16 v[88:91], v[144:147], v[196:199], v[92:95]
	v_mfma_f32_16x16x32_bf16 v[20:23], v[152:155], v[196:199], v[20:23]
	v_mfma_f32_16x16x32_bf16 v[28:31], v[144:147], v[160:163], v[120:123]
	v_mfma_f32_16x16x32_bf16 v[48:51], v[156:159], v[164:167], v[48:51]
	v_mfma_f32_16x16x32_bf16 v[72:75], v[148:151], v[172:175], v[72:75]
	v_mfma_f32_16x16x32_bf16 v[8:11], v[156:159], v[172:175], v[8:11]
	v_mfma_f32_16x16x32_bf16 v[64:67], v[148:151], v[180:183], v[64:67]
	v_mfma_f32_16x16x32_bf16 v[0:3], v[156:159], v[180:183], v[0:3]
	v_mfma_f32_16x16x32_bf16 v[92:95], v[148:151], v[200:203], v[88:91]
	v_mfma_f32_16x16x32_bf16 v[20:23], v[156:159], v[200:203], v[20:23]
	v_mfma_f32_16x16x32_bf16 v[28:31], v[148:151], v[164:167], v[28:31]
	s_barrier
	s_add_i32 s23, 0, 0x18000
	s_add_i32 s24, 0, 0x1c000
	v_add_u32_e32 v120, s23, v222
	v_add_u32_e32 v156, s24, v222
	ds_read_b128 v[88:91], v120
	ds_read_b128 v[96:99], v120 offset:1024
	ds_read_b128 v[100:103], v120 offset:2048
	ds_read_b128 v[120:123], v120 offset:3072
	ds_read_b128 v[144:147], v156
	ds_read_b128 v[148:151], v156 offset:1024
	ds_read_b128 v[152:155], v156 offset:2048
	ds_read_b128 v[156:159], v156 offset:3072
	s_add_u32 s18, s18, 0x80000
	s_addc_u32 s19, s19, 0
	s_mov_b32 m0, s33
	v_lshl_add_u64 v[212:213], s[18:19], 0, v[190:191]
	ds_read_b128 v[160:163], v236 offset:32768
	ds_read_b128 v[164:167], v236 offset:33792
	ds_read_b128 v[168:171], v236 offset:34816
	ds_read_b128 v[172:175], v236 offset:35840
	ds_read_b128 v[176:179], v236 offset:36864
	ds_read_b128 v[180:183], v236 offset:37888
	ds_read_b128 v[196:199], v236 offset:38912
	ds_read_b128 v[200:203], v236 offset:39936
	global_load_lds_dwordx4 v[212:213], off
	v_lshl_add_u64 v[212:213], s[18:19], 0, v[186:187]
	s_mov_b32 m0, s30
	s_nop 0
	global_load_lds_dwordx4 v[212:213], off
	s_waitcnt vmcnt(8)
	s_waitcnt lgkmcnt(0)
	s_barrier
	s_waitcnt lgkmcnt(0)
	v_mfma_f32_16x16x32_bf16 v[140:143], v[88:91], v[160:163], v[140:143]
	v_mfma_f32_16x16x32_bf16 v[84:87], v[100:103], v[160:163], v[84:87]
	v_mfma_f32_16x16x32_bf16 v[116:119], v[88:91], v[168:171], v[116:119]
	v_mfma_f32_16x16x32_bf16 v[44:47], v[100:103], v[168:171], v[44:47]
	v_mfma_f32_16x16x32_bf16 v[108:111], v[88:91], v[176:179], v[108:111]
	v_mfma_f32_16x16x32_bf16 v[36:39], v[100:103], v[176:179], v[36:39]
	v_mfma_f32_16x16x32_bf16 v[136:139], v[88:91], v[196:199], v[136:139]
	v_mfma_f32_16x16x32_bf16 v[56:59], v[100:103], v[196:199], v[56:59]
	v_mfma_f32_16x16x32_bf16 v[140:143], v[96:99], v[164:167], v[140:143]
	v_mfma_f32_16x16x32_bf16 v[84:87], v[120:123], v[164:167], v[84:87]
	v_mfma_f32_16x16x32_bf16 v[116:119], v[96:99], v[172:175], v[116:119]
	v_mfma_f32_16x16x32_bf16 v[44:47], v[120:123], v[172:175], v[44:47]
	v_mfma_f32_16x16x32_bf16 v[108:111], v[96:99], v[180:183], v[108:111]
	v_mfma_f32_16x16x32_bf16 v[36:39], v[120:123], v[180:183], v[36:39]
	v_mfma_f32_16x16x32_bf16 v[136:139], v[96:99], v[200:203], v[136:139]
	v_mfma_f32_16x16x32_bf16 v[56:59], v[120:123], v[200:203], v[56:59]
	v_mfma_f32_16x16x32_bf16 v[128:131], v[144:147], v[160:163], v[128:131]
	v_mfma_f32_16x16x32_bf16 v[80:83], v[152:155], v[160:163], v[80:83]
	v_mfma_f32_16x16x32_bf16 v[112:115], v[144:147], v[168:171], v[112:115]
	v_mfma_f32_16x16x32_bf16 v[40:43], v[152:155], v[168:171], v[40:43]
	v_mfma_f32_16x16x32_bf16 v[104:107], v[144:147], v[176:179], v[104:107]
	v_mfma_f32_16x16x32_bf16 v[32:35], v[152:155], v[176:179], v[32:35]
	v_mfma_f32_16x16x32_bf16 v[132:135], v[144:147], v[196:199], v[132:135]
	v_mfma_f32_16x16x32_bf16 v[60:63], v[152:155], v[196:199], v[60:63]
	v_mfma_f32_16x16x32_bf16 v[128:131], v[148:151], v[164:167], v[128:131]
	v_mfma_f32_16x16x32_bf16 v[80:83], v[156:159], v[164:167], v[80:83]
	v_mfma_f32_16x16x32_bf16 v[112:115], v[148:151], v[172:175], v[112:115]
	v_mfma_f32_16x16x32_bf16 v[40:43], v[156:159], v[172:175], v[40:43]
	v_mfma_f32_16x16x32_bf16 v[104:107], v[148:151], v[180:183], v[104:107]
	v_mfma_f32_16x16x32_bf16 v[32:35], v[156:159], v[180:183], v[32:35]
	v_mfma_f32_16x16x32_bf16 v[132:135], v[148:151], v[200:203], v[132:135]
	v_mfma_f32_16x16x32_bf16 v[60:63], v[156:159], v[200:203], v[60:63]
	s_barrier
	s_add_i32 s18, s23, s51
	v_lshl_add_u64 v[204:205], v[204:205], 0, s[58:59]
	s_mov_b32 m0, s18
	ds_read_b128 v[160:163], v236 offset:49152
	ds_read_b128 v[164:167], v236 offset:50176
	ds_read_b128 v[168:171], v236 offset:51200
	ds_read_b128 v[172:175], v236 offset:52224
	ds_read_b128 v[176:179], v236 offset:53248
	ds_read_b128 v[180:183], v236 offset:54272
	ds_read_b128 v[196:199], v236 offset:55296
	ds_read_b128 v[200:203], v236 offset:56320
	global_load_lds_dwordx4 v[204:205], off
	s_add_i32 m0, s18, 0x2000
	s_add_u32 s16, s16, 0x84080
	v_lshl_add_u64 v[204:205], v[206:207], 0, s[58:59]
	s_addc_u32 s17, s17, 0
	s_add_i32 s18, s24, s51
	global_load_lds_dwordx4 v[204:205], off
	v_lshl_add_u64 v[204:205], s[16:17], 0, v[188:189]
	s_mov_b32 m0, s18
	s_nop 0
	global_load_lds_dwordx4 v[204:205], off
	v_lshl_add_u64 v[204:205], s[16:17], 0, v[184:185]
	s_add_i32 m0, s18, 0x2000
	s_nop 0
	global_load_lds_dwordx4 v[204:205], off
	v_lshl_add_u64 v[204:205], v[208:209], 0, s[58:59]
	s_mov_b32 m0, s31
	s_nop 0
	global_load_lds_dwordx4 v[204:205], off
	v_lshl_add_u64 v[204:205], v[210:211], 0, s[58:59]
	s_mov_b32 m0, s38
	s_nop 0
	global_load_lds_dwordx4 v[204:205], off
	s_waitcnt vmcnt(8)
	s_waitcnt lgkmcnt(0)
	s_barrier
	s_waitcnt lgkmcnt(0)
	v_mfma_f32_16x16x32_bf16 v[124:127], v[88:91], v[160:163], v[124:127]
	v_mfma_f32_16x16x32_bf16 v[52:55], v[100:103], v[160:163], v[52:55]
	v_mfma_f32_16x16x32_bf16 v[76:79], v[88:91], v[168:171], v[76:79]
	v_mfma_f32_16x16x32_bf16 v[12:15], v[100:103], v[168:171], v[12:15]
	v_mfma_f32_16x16x32_bf16 v[68:71], v[88:91], v[176:179], v[68:71]
	v_mfma_f32_16x16x32_bf16 v[4:7], v[100:103], v[176:179], v[4:7]
	v_mfma_f32_16x16x32_bf16 v[24:27], v[88:91], v[196:199], v[24:27]
	v_mfma_f32_16x16x32_bf16 v[16:19], v[100:103], v[196:199], v[16:19]
	v_mfma_f32_16x16x32_bf16 v[124:127], v[96:99], v[164:167], v[124:127]
	v_mfma_f32_16x16x32_bf16 v[52:55], v[120:123], v[164:167], v[52:55]
	v_mfma_f32_16x16x32_bf16 v[76:79], v[96:99], v[172:175], v[76:79]
	v_mfma_f32_16x16x32_bf16 v[12:15], v[120:123], v[172:175], v[12:15]
	v_mfma_f32_16x16x32_bf16 v[68:71], v[96:99], v[180:183], v[68:71]
	v_mfma_f32_16x16x32_bf16 v[4:7], v[120:123], v[180:183], v[4:7]
	v_mfma_f32_16x16x32_bf16 v[88:91], v[96:99], v[200:203], v[24:27]
	v_mfma_f32_16x16x32_bf16 v[16:19], v[120:123], v[200:203], v[16:19]
	v_mfma_f32_16x16x32_bf16 v[24:27], v[144:147], v[160:163], v[28:31]
	v_mfma_f32_16x16x32_bf16 v[120:123], v[148:151], v[164:167], v[24:27]
	v_mfma_f32_16x16x32_bf16 v[24:27], v[152:155], v[160:163], v[48:51]
	v_mfma_f32_16x16x32_bf16 v[48:51], v[156:159], v[164:167], v[24:27]
	v_mfma_f32_16x16x32_bf16 v[24:27], v[144:147], v[168:171], v[72:75]
	v_mfma_f32_16x16x32_bf16 v[72:75], v[148:151], v[172:175], v[24:27]
	v_mfma_f32_16x16x32_bf16 v[24:27], v[144:147], v[176:179], v[64:67]
	v_mfma_f32_16x16x32_bf16 v[8:11], v[152:155], v[168:171], v[8:11]
	v_mfma_f32_16x16x32_bf16 v[64:67], v[148:151], v[180:183], v[24:27]
	v_mfma_f32_16x16x32_bf16 v[0:3], v[152:155], v[176:179], v[0:3]
	v_mfma_f32_16x16x32_bf16 v[24:27], v[144:147], v[196:199], v[92:95]
	v_mfma_f32_16x16x32_bf16 v[20:23], v[152:155], v[196:199], v[20:23]
	v_mfma_f32_16x16x32_bf16 v[8:11], v[156:159], v[172:175], v[8:11]
	v_mfma_f32_16x16x32_bf16 v[0:3], v[156:159], v[180:183], v[0:3]
	v_mfma_f32_16x16x32_bf16 v[92:95], v[148:151], v[200:203], v[24:27]
	v_mfma_f32_16x16x32_bf16 v[20:23], v[156:159], v[200:203], v[20:23]
	s_barrier
	s_add_i32 s22, s22, 2
	s_add_u32 s14, s14, 0x100
	s_addc_u32 s15, s15, 0
	s_add_u32 s20, s20, 0x100
	s_addc_u32 s21, s21, 0
	s_cmp_gt_u32 s22, 29
	s_cbranch_scc0 .LBB0_1391
	s_and_b64 vcc, exec, s[82:83]
	s_cbranch_vccz .LBB0_1394
	s_barrier

.LBB0_1626:
	ds_read_b128 v[128:131], v224
	ds_read_b128 v[132:135], v224 offset:1024
	ds_read_b128 v[136:139], v224 offset:2048
	ds_read_b128 v[140:143], v224 offset:3072
	ds_read_b128 v[154:157], v225
	ds_read_b128 v[158:161], v225 offset:1024
	ds_read_b128 v[162:165], v225 offset:2048
	ds_read_b128 v[166:169], v225 offset:3072
	s_add_i32 s48, s34, 2
	s_add_u32 s35, s26, 0xffea0080
	s_addc_u32 s49, s27, -1
	s_cmp_eq_u32 s30, s34
	s_cselect_b32 s34, s54, s31
	s_cselect_b32 s61, s53, s49
	s_cselect_b32 s60, s52, s35
	s_cselect_b32 s35, s55, s33
	v_lshl_add_u64 v[202:203], s[26:27], 0, v[150:151]
	s_add_i32 m0, s66, 0xc000
	ds_read_b128 v[170:173], v226
	ds_read_b128 v[174:177], v226 offset:1024
	ds_read_b128 v[178:181], v226 offset:2048
	ds_read_b128 v[182:185], v226 offset:3072
	ds_read_b128 v[186:189], v226 offset:4096
	ds_read_b128 v[190:193], v226 offset:5120
	ds_read_b128 v[194:197], v226 offset:6144
	ds_read_b128 v[198:201], v226 offset:7168
	global_load_lds_dwordx4 v[202:203], off
	v_lshl_add_u64 v[202:203], s[26:27], 0, v[152:153]
	s_add_i32 m0, s66, 0xe000
	s_nop 0
	global_load_lds_dwordx4 v[202:203], off
	s_waitcnt vmcnt(8)
	s_waitcnt lgkmcnt(0)
	s_barrier
	s_waitcnt lgkmcnt(0)
	v_mfma_f32_16x16x32_bf16 v[124:127], v[128:131], v[170:173], v[124:127]
	v_mfma_f32_16x16x32_bf16 v[120:123], v[136:139], v[170:173], v[120:123]
	v_mfma_f32_16x16x32_bf16 v[112:115], v[128:131], v[178:181], v[112:115]
	v_mfma_f32_16x16x32_bf16 v[104:107], v[136:139], v[178:181], v[104:107]
	v_mfma_f32_16x16x32_bf16 v[96:99], v[128:131], v[186:189], v[96:99]
	v_mfma_f32_16x16x32_bf16 v[88:91], v[136:139], v[186:189], v[88:91]
	v_mfma_f32_16x16x32_bf16 v[80:83], v[128:131], v[194:197], v[80:83]
	v_mfma_f32_16x16x32_bf16 v[72:75], v[136:139], v[194:197], v[72:75]
	v_mfma_f32_16x16x32_bf16 v[124:127], v[132:135], v[174:177], v[124:127]
	v_mfma_f32_16x16x32_bf16 v[120:123], v[140:143], v[174:177], v[120:123]
	v_mfma_f32_16x16x32_bf16 v[112:115], v[132:135], v[182:185], v[112:115]
	v_mfma_f32_16x16x32_bf16 v[104:107], v[140:143], v[182:185], v[104:107]
	v_mfma_f32_16x16x32_bf16 v[96:99], v[132:135], v[190:193], v[96:99]
	v_mfma_f32_16x16x32_bf16 v[88:91], v[140:143], v[190:193], v[88:91]
	v_mfma_f32_16x16x32_bf16 v[80:83], v[132:135], v[198:201], v[80:83]
	v_mfma_f32_16x16x32_bf16 v[72:75], v[140:143], v[198:201], v[72:75]
	v_mfma_f32_16x16x32_bf16 v[116:119], v[154:157], v[170:173], v[116:119]
	v_mfma_f32_16x16x32_bf16 v[108:111], v[162:165], v[170:173], v[108:111]
	v_mfma_f32_16x16x32_bf16 v[100:103], v[154:157], v[178:181], v[100:103]
	v_mfma_f32_16x16x32_bf16 v[92:95], v[162:165], v[178:181], v[92:95]
	v_mfma_f32_16x16x32_bf16 v[84:87], v[154:157], v[186:189], v[84:87]
	v_mfma_f32_16x16x32_bf16 v[76:79], v[162:165], v[186:189], v[76:79]
	v_mfma_f32_16x16x32_bf16 v[68:71], v[154:157], v[194:197], v[68:71]
	v_mfma_f32_16x16x32_bf16 v[64:67], v[162:165], v[194:197], v[64:67]
	v_mfma_f32_16x16x32_bf16 v[116:119], v[158:161], v[174:177], v[116:119]
	v_mfma_f32_16x16x32_bf16 v[108:111], v[166:169], v[174:177], v[108:111]
	v_mfma_f32_16x16x32_bf16 v[100:103], v[158:161], v[182:185], v[100:103]
	v_mfma_f32_16x16x32_bf16 v[92:95], v[166:169], v[182:185], v[92:95]
	v_mfma_f32_16x16x32_bf16 v[84:87], v[158:161], v[190:193], v[84:87]
	v_mfma_f32_16x16x32_bf16 v[76:79], v[166:169], v[190:193], v[76:79]
	v_mfma_f32_16x16x32_bf16 v[68:71], v[158:161], v[198:201], v[68:71]
	v_mfma_f32_16x16x32_bf16 v[64:67], v[166:169], v[198:201], v[64:67]
	s_barrier
	s_add_i32 s49, s79, s65
	v_lshl_add_u64 v[202:203], s[34:35], 0, v[144:145]
	s_mov_b32 m0, s49
	ds_read_b128 v[170:173], v226 offset:16384
	ds_read_b128 v[174:177], v226 offset:17408
	ds_read_b128 v[178:181], v226 offset:18432
	ds_read_b128 v[182:185], v226 offset:19456
	ds_read_b128 v[186:189], v226 offset:20480
	ds_read_b128 v[190:193], v226 offset:21504
	ds_read_b128 v[194:197], v226 offset:22528
	ds_read_b128 v[198:201], v226 offset:23552
	global_load_lds_dwordx4 v[202:203], off
	s_add_i32 m0, s49, 0x2000
	s_add_u32 s50, s34, 0x160000
	v_lshl_add_u64 v[204:205], s[34:35], 0, v[146:147]
	s_addc_u32 s51, s35, 0
	s_add_i32 s49, s84, s65
	global_load_lds_dwordx4 v[204:205], off
	v_lshl_add_u64 v[206:207], s[50:51], 0, v[144:145]
	s_mov_b32 m0, s49
	v_lshl_add_u64 v[208:209], s[60:61], 0, v[146:147]
	global_load_lds_dwordx4 v[206:207], off
	v_lshl_add_u64 v[206:207], s[50:51], 0, v[146:147]
	s_add_i32 m0, s49, 0x2000
	s_nop 0
	global_load_lds_dwordx4 v[206:207], off
	v_lshl_add_u64 v[206:207], s[60:61], 0, v[144:145]
	s_mov_b32 m0, s66
	s_nop 0
	global_load_lds_dwordx4 v[206:207], off
	s_mov_b32 m0, s67
	s_nop 0
	global_load_lds_dwordx4 v[208:209], off
	s_waitcnt vmcnt(8)
	s_waitcnt lgkmcnt(0)
	s_barrier
	s_waitcnt lgkmcnt(0)
	v_mfma_f32_16x16x32_bf16 v[60:63], v[128:131], v[170:173], v[60:63]
	v_mfma_f32_16x16x32_bf16 v[56:59], v[136:139], v[170:173], v[56:59]
	v_mfma_f32_16x16x32_bf16 v[48:51], v[128:131], v[178:181], v[48:51]
	v_mfma_f32_16x16x32_bf16 v[40:43], v[136:139], v[178:181], v[40:43]
	v_mfma_f32_16x16x32_bf16 v[32:35], v[128:131], v[186:189], v[32:35]
	v_mfma_f32_16x16x32_bf16 v[24:27], v[136:139], v[186:189], v[24:27]
	v_mfma_f32_16x16x32_bf16 v[16:19], v[128:131], v[194:197], v[16:19]
	v_mfma_f32_16x16x32_bf16 v[8:11], v[136:139], v[194:197], v[8:11]
	v_mfma_f32_16x16x32_bf16 v[60:63], v[132:135], v[174:177], v[60:63]
	v_mfma_f32_16x16x32_bf16 v[56:59], v[140:143], v[174:177], v[56:59]
	v_mfma_f32_16x16x32_bf16 v[48:51], v[132:135], v[182:185], v[48:51]
	v_mfma_f32_16x16x32_bf16 v[40:43], v[140:143], v[182:185], v[40:43]
	v_mfma_f32_16x16x32_bf16 v[32:35], v[132:135], v[190:193], v[32:35]
	v_mfma_f32_16x16x32_bf16 v[24:27], v[140:143], v[190:193], v[24:27]
	v_mfma_f32_16x16x32_bf16 v[16:19], v[132:135], v[198:201], v[16:19]
	v_mfma_f32_16x16x32_bf16 v[8:11], v[140:143], v[198:201], v[8:11]
	v_mfma_f32_16x16x32_bf16 v[52:55], v[154:157], v[170:173], v[52:55]
	v_mfma_f32_16x16x32_bf16 v[44:47], v[162:165], v[170:173], v[44:47]
	v_mfma_f32_16x16x32_bf16 v[36:39], v[154:157], v[178:181], v[36:39]
	v_mfma_f32_16x16x32_bf16 v[28:31], v[162:165], v[178:181], v[28:31]
	v_mfma_f32_16x16x32_bf16 v[20:23], v[154:157], v[186:189], v[20:23]
	v_mfma_f32_16x16x32_bf16 v[12:15], v[162:165], v[186:189], v[12:15]
	v_mfma_f32_16x16x32_bf16 v[4:7], v[154:157], v[194:197], v[4:7]
	v_mfma_f32_16x16x32_bf16 v[0:3], v[162:165], v[194:197], v[0:3]
	v_mfma_f32_16x16x32_bf16 v[52:55], v[158:161], v[174:177], v[52:55]
	v_mfma_f32_16x16x32_bf16 v[44:47], v[166:169], v[174:177], v[44:47]
	v_mfma_f32_16x16x32_bf16 v[36:39], v[158:161], v[182:185], v[36:39]
	v_mfma_f32_16x16x32_bf16 v[28:31], v[166:169], v[182:185], v[28:31]
	v_mfma_f32_16x16x32_bf16 v[20:23], v[158:161], v[190:193], v[20:23]
	v_mfma_f32_16x16x32_bf16 v[12:15], v[166:169], v[190:193], v[12:15]
	v_mfma_f32_16x16x32_bf16 v[4:7], v[158:161], v[198:201], v[4:7]
	v_mfma_f32_16x16x32_bf16 v[0:3], v[166:169], v[198:201], v[0:3]
	s_barrier
	s_add_i32 s49, 0, 0x18000
	s_add_i32 s57, 0, 0x1c000
	v_add_u32_e32 v140, s49, v220
	v_add_u32_e32 v166, s57, v220
	ds_read_b128 v[128:131], v140
	ds_read_b128 v[132:135], v140 offset:1024
	ds_read_b128 v[136:139], v140 offset:2048
	ds_read_b128 v[140:143], v140 offset:3072
	ds_read_b128 v[154:157], v166
	ds_read_b128 v[158:161], v166 offset:1024
	ds_read_b128 v[162:165], v166 offset:2048
	ds_read_b128 v[166:169], v166 offset:3072
	s_add_u32 s50, s60, 0x160000
	s_addc_u32 s51, s61, 0
	s_mov_b32 m0, s68
	v_lshl_add_u64 v[210:211], s[50:51], 0, v[144:145]
	ds_read_b128 v[170:173], v226 offset:32768
	ds_read_b128 v[174:177], v226 offset:33792
	ds_read_b128 v[178:181], v226 offset:34816
	ds_read_b128 v[182:185], v226 offset:35840
	ds_read_b128 v[186:189], v226 offset:36864
	ds_read_b128 v[190:193], v226 offset:37888
	ds_read_b128 v[194:197], v226 offset:38912
	ds_read_b128 v[198:201], v226 offset:39936
	global_load_lds_dwordx4 v[210:211], off
	v_lshl_add_u64 v[210:211], s[50:51], 0, v[146:147]
	s_mov_b32 m0, s69
	s_nop 0
	global_load_lds_dwordx4 v[210:211], off
	s_waitcnt vmcnt(8)
	s_waitcnt lgkmcnt(0)
	s_barrier
	s_waitcnt lgkmcnt(0)
	v_mfma_f32_16x16x32_bf16 v[124:127], v[128:131], v[170:173], v[124:127]
	v_mfma_f32_16x16x32_bf16 v[120:123], v[136:139], v[170:173], v[120:123]
	v_mfma_f32_16x16x32_bf16 v[112:115], v[128:131], v[178:181], v[112:115]
	v_mfma_f32_16x16x32_bf16 v[104:107], v[136:139], v[178:181], v[104:107]
	v_mfma_f32_16x16x32_bf16 v[96:99], v[128:131], v[186:189], v[96:99]
	v_mfma_f32_16x16x32_bf16 v[88:91], v[136:139], v[186:189], v[88:91]
	v_mfma_f32_16x16x32_bf16 v[80:83], v[128:131], v[194:197], v[80:83]
	v_mfma_f32_16x16x32_bf16 v[72:75], v[136:139], v[194:197], v[72:75]
	v_mfma_f32_16x16x32_bf16 v[124:127], v[132:135], v[174:177], v[124:127]
	v_mfma_f32_16x16x32_bf16 v[120:123], v[140:143], v[174:177], v[120:123]
	v_mfma_f32_16x16x32_bf16 v[112:115], v[132:135], v[182:185], v[112:115]
	v_mfma_f32_16x16x32_bf16 v[104:107], v[140:143], v[182:185], v[104:107]
	v_mfma_f32_16x16x32_bf16 v[96:99], v[132:135], v[190:193], v[96:99]
	v_mfma_f32_16x16x32_bf16 v[88:91], v[140:143], v[190:193], v[88:91]
	v_mfma_f32_16x16x32_bf16 v[80:83], v[132:135], v[198:201], v[80:83]
	v_mfma_f32_16x16x32_bf16 v[72:75], v[140:143], v[198:201], v[72:75]
	v_mfma_f32_16x16x32_bf16 v[116:119], v[154:157], v[170:173], v[116:119]
	v_mfma_f32_16x16x32_bf16 v[108:111], v[162:165], v[170:173], v[108:111]
	v_mfma_f32_16x16x32_bf16 v[100:103], v[154:157], v[178:181], v[100:103]
	v_mfma_f32_16x16x32_bf16 v[92:95], v[162:165], v[178:181], v[92:95]
	v_mfma_f32_16x16x32_bf16 v[84:87], v[154:157], v[186:189], v[84:87]
	v_mfma_f32_16x16x32_bf16 v[76:79], v[162:165], v[186:189], v[76:79]
	v_mfma_f32_16x16x32_bf16 v[68:71], v[154:157], v[194:197], v[68:71]
	v_mfma_f32_16x16x32_bf16 v[64:67], v[162:165], v[194:197], v[64:67]
	v_mfma_f32_16x16x32_bf16 v[116:119], v[158:161], v[174:177], v[116:119]
	v_mfma_f32_16x16x32_bf16 v[108:111], v[166:169], v[174:177], v[108:111]
	v_mfma_f32_16x16x32_bf16 v[100:103], v[158:161], v[182:185], v[100:103]
	v_mfma_f32_16x16x32_bf16 v[92:95], v[166:169], v[182:185], v[92:95]
	v_mfma_f32_16x16x32_bf16 v[84:87], v[158:161], v[190:193], v[84:87]
	v_mfma_f32_16x16x32_bf16 v[76:79], v[166:169], v[190:193], v[76:79]
	v_mfma_f32_16x16x32_bf16 v[68:71], v[158:161], v[198:201], v[68:71]
	v_mfma_f32_16x16x32_bf16 v[64:67], v[166:169], v[198:201], v[64:67]
	s_barrier
	s_add_i32 s49, s49, s65
	v_lshl_add_u64 v[202:203], v[202:203], 0, s[24:25]
	s_mov_b32 m0, s49
	ds_read_b128 v[170:173], v226 offset:49152
	ds_read_b128 v[174:177], v226 offset:50176
	ds_read_b128 v[178:181], v226 offset:51200
	ds_read_b128 v[182:185], v226 offset:52224
	ds_read_b128 v[186:189], v226 offset:53248
	ds_read_b128 v[190:193], v226 offset:54272
	ds_read_b128 v[194:197], v226 offset:55296
	ds_read_b128 v[198:201], v226 offset:56320
	global_load_lds_dwordx4 v[202:203], off
	s_add_i32 m0, s49, 0x2000
	s_add_u32 s34, s34, 0x160080
	v_lshl_add_u64 v[202:203], v[204:205], 0, s[24:25]
	s_addc_u32 s35, s35, 0
	s_add_i32 s49, s57, s65
	global_load_lds_dwordx4 v[202:203], off
	v_lshl_add_u64 v[202:203], s[34:35], 0, v[144:145]
	s_mov_b32 m0, s49
	s_nop 0
	global_load_lds_dwordx4 v[202:203], off
	v_lshl_add_u64 v[202:203], s[34:35], 0, v[146:147]
	s_add_i32 m0, s49, 0x2000
	s_nop 0
	global_load_lds_dwordx4 v[202:203], off
	v_lshl_add_u64 v[202:203], v[206:207], 0, s[24:25]
	s_mov_b32 m0, s74
	s_nop 0
	global_load_lds_dwordx4 v[202:203], off
	v_lshl_add_u64 v[202:203], v[208:209], 0, s[24:25]
	s_mov_b32 m0, s75
	s_nop 0
	global_load_lds_dwordx4 v[202:203], off
	s_waitcnt vmcnt(8)
	s_waitcnt lgkmcnt(0)
	s_barrier
	s_waitcnt lgkmcnt(0)
	v_mfma_f32_16x16x32_bf16 v[60:63], v[128:131], v[170:173], v[60:63]
	v_mfma_f32_16x16x32_bf16 v[56:59], v[136:139], v[170:173], v[56:59]
	v_mfma_f32_16x16x32_bf16 v[48:51], v[128:131], v[178:181], v[48:51]
	v_mfma_f32_16x16x32_bf16 v[40:43], v[136:139], v[178:181], v[40:43]
	v_mfma_f32_16x16x32_bf16 v[32:35], v[128:131], v[186:189], v[32:35]
	v_mfma_f32_16x16x32_bf16 v[24:27], v[136:139], v[186:189], v[24:27]
	v_mfma_f32_16x16x32_bf16 v[16:19], v[128:131], v[194:197], v[16:19]
	v_mfma_f32_16x16x32_bf16 v[8:11], v[136:139], v[194:197], v[8:11]
	v_mfma_f32_16x16x32_bf16 v[60:63], v[132:135], v[174:177], v[60:63]
	v_mfma_f32_16x16x32_bf16 v[56:59], v[140:143], v[174:177], v[56:59]
	v_mfma_f32_16x16x32_bf16 v[48:51], v[132:135], v[182:185], v[48:51]
	v_mfma_f32_16x16x32_bf16 v[40:43], v[140:143], v[182:185], v[40:43]
	v_mfma_f32_16x16x32_bf16 v[32:35], v[132:135], v[190:193], v[32:35]
	v_mfma_f32_16x16x32_bf16 v[24:27], v[140:143], v[190:193], v[24:27]
	v_mfma_f32_16x16x32_bf16 v[16:19], v[132:135], v[198:201], v[16:19]
	v_mfma_f32_16x16x32_bf16 v[8:11], v[140:143], v[198:201], v[8:11]
	v_mfma_f32_16x16x32_bf16 v[52:55], v[154:157], v[170:173], v[52:55]
	v_mfma_f32_16x16x32_bf16 v[44:47], v[162:165], v[170:173], v[44:47]
	v_mfma_f32_16x16x32_bf16 v[36:39], v[154:157], v[178:181], v[36:39]
	v_mfma_f32_16x16x32_bf16 v[28:31], v[162:165], v[178:181], v[28:31]
	v_mfma_f32_16x16x32_bf16 v[20:23], v[154:157], v[186:189], v[20:23]
	v_mfma_f32_16x16x32_bf16 v[12:15], v[162:165], v[186:189], v[12:15]
	v_mfma_f32_16x16x32_bf16 v[4:7], v[154:157], v[194:197], v[4:7]
	v_mfma_f32_16x16x32_bf16 v[0:3], v[162:165], v[194:197], v[0:3]
	v_mfma_f32_16x16x32_bf16 v[52:55], v[158:161], v[174:177], v[52:55]
	v_mfma_f32_16x16x32_bf16 v[44:47], v[166:169], v[174:177], v[44:47]
	v_mfma_f32_16x16x32_bf16 v[36:39], v[158:161], v[182:185], v[36:39]
	v_mfma_f32_16x16x32_bf16 v[28:31], v[166:169], v[182:185], v[28:31]
	v_mfma_f32_16x16x32_bf16 v[20:23], v[158:161], v[190:193], v[20:23]
	v_mfma_f32_16x16x32_bf16 v[12:15], v[166:169], v[190:193], v[12:15]
	v_mfma_f32_16x16x32_bf16 v[4:7], v[158:161], v[198:201], v[4:7]
	v_mfma_f32_16x16x32_bf16 v[0:3], v[166:169], v[198:201], v[0:3]
	s_barrier
	s_add_u32 s26, s26, 0x100
	s_addc_u32 s27, s27, 0
	s_add_u32 s31, s31, 0x100
	s_addc_u32 s33, s33, 0
	s_cmp_ge_u32 s48, s16
	s_mov_b32 s34, s48
	s_cbranch_scc0 .LBB0_1626
	s_and_b64 vcc, exec, s[28:29]
	s_cbranch_vccz .LBB0_1629
	s_barrier
